# waitcnt clean-up: 48 back-to-back duplicate s_waitcnt lgkmcnt(0) removed from the four GEMM phases
# speedup vs baseline: 1.0057x; 1.0057x over previous
.LBB0_171:
	ds_read_b128 v[176:179], v167
	ds_read_b128 v[180:183], v167 offset:1024
	ds_read_b128 v[184:187], v167 offset:2048
	ds_read_b128 v[188:191], v167 offset:3072
	v_add_u32_e32 v157, 0xc000, v161
	v_lshl_add_u64 v[196:197], s[10:11], 0, v[148:149]
	v_readfirstlane_b32 s4, v157
	v_add_u32_e32 v175, 0xe000, v161
	v_lshl_add_u64 v[228:229], v[196:197], 0, s[36:37]
	s_mov_b32 m0, s4
	v_lshl_add_u64 v[244:245], s[10:11], 0, v[150:151]
	v_readfirstlane_b32 s4, v175
	ds_read_b128 v[192:195], v168
	ds_read_b128 v[200:203], v168 offset:1024
	ds_read_b128 v[204:207], v169
	ds_read_b128 v[208:211], v169 offset:1024
	ds_read_b128 v[212:215], v170
	ds_read_b128 v[216:219], v170 offset:1024
	ds_read_b128 v[220:223], v171
	ds_read_b128 v[224:227], v171 offset:1024
	global_load_lds_dwordx4 v[228:229], off
	v_lshl_add_u64 v[228:229], v[244:245], 0, s[36:37]
	s_mov_b32 m0, s4
	s_nop 0
	global_load_lds_dwordx4 v[228:229], off
	s_waitcnt lgkmcnt(8)
	s_barrier
	s_waitcnt lgkmcnt(0)
	v_mfma_f32_16x16x32_bf16 v[126:129], v[176:179], v[192:195], v[126:129]
	v_mfma_f32_16x16x32_bf16 v[122:125], v[184:187], v[192:195], v[122:125]
	v_mfma_f32_16x16x32_bf16 v[118:121], v[176:179], v[204:207], v[118:121]
	v_mfma_f32_16x16x32_bf16 v[114:117], v[184:187], v[204:207], v[114:117]
	v_mfma_f32_16x16x32_bf16 v[110:113], v[176:179], v[212:215], v[110:113]
	v_mfma_f32_16x16x32_bf16 v[106:109], v[184:187], v[212:215], v[106:109]
	v_mfma_f32_16x16x32_bf16 v[102:105], v[176:179], v[220:223], v[102:105]
	v_mfma_f32_16x16x32_bf16 v[98:101], v[184:187], v[220:223], v[98:101]
	v_mfma_f32_16x16x32_bf16 v[126:129], v[180:183], v[200:203], v[126:129]
	v_mfma_f32_16x16x32_bf16 v[122:125], v[188:191], v[200:203], v[122:125]
	v_mfma_f32_16x16x32_bf16 v[118:121], v[180:183], v[208:211], v[118:121]
	v_mfma_f32_16x16x32_bf16 v[114:117], v[188:191], v[208:211], v[114:117]
	v_mfma_f32_16x16x32_bf16 v[110:113], v[180:183], v[216:219], v[110:113]
	v_mfma_f32_16x16x32_bf16 v[106:109], v[188:191], v[216:219], v[106:109]
	v_mfma_f32_16x16x32_bf16 v[102:105], v[180:183], v[224:227], v[102:105]
	v_mfma_f32_16x16x32_bf16 v[98:101], v[188:191], v[224:227], v[98:101]
	s_barrier
	v_lshl_add_u64 v[246:247], s[10:11], 0, v[144:145]
	v_readfirstlane_b32 s4, v159
	v_lshl_add_u64 v[248:249], v[246:247], 0, s[38:39]
	s_mov_b32 m0, s4
	ds_read_b128 v[228:231], v172
	ds_read_b128 v[232:235], v172 offset:1024
	ds_read_b128 v[236:239], v172 offset:2048
	ds_read_b128 v[240:243], v172 offset:3072
	global_load_lds_dwordx4 v[248:249], off
	v_lshl_add_u64 v[248:249], s[10:11], 0, v[146:147]
	v_readfirstlane_b32 s4, v160
	v_lshl_add_u64 v[250:251], v[248:249], 0, s[38:39]
	s_mov_b32 m0, s4
	s_nop 0
	global_load_lds_dwordx4 v[250:251], off
	s_barrier
	s_waitcnt lgkmcnt(0)
	v_mfma_f32_16x16x32_bf16 v[94:97], v[228:231], v[192:195], v[94:97]
	v_mfma_f32_16x16x32_bf16 v[90:93], v[236:239], v[192:195], v[90:93]
	v_mfma_f32_16x16x32_bf16 v[86:89], v[228:231], v[204:207], v[86:89]
	v_mfma_f32_16x16x32_bf16 v[82:85], v[236:239], v[204:207], v[82:85]
	v_mfma_f32_16x16x32_bf16 v[78:81], v[228:231], v[212:215], v[78:81]
	v_mfma_f32_16x16x32_bf16 v[74:77], v[236:239], v[212:215], v[74:77]
	v_mfma_f32_16x16x32_bf16 v[70:73], v[228:231], v[220:223], v[70:73]
	v_mfma_f32_16x16x32_bf16 v[66:69], v[236:239], v[220:223], v[66:69]
	v_mfma_f32_16x16x32_bf16 v[94:97], v[232:235], v[200:203], v[94:97]
	v_mfma_f32_16x16x32_bf16 v[90:93], v[240:243], v[200:203], v[90:93]
	v_mfma_f32_16x16x32_bf16 v[86:89], v[232:235], v[208:211], v[86:89]
	v_mfma_f32_16x16x32_bf16 v[82:85], v[240:243], v[208:211], v[82:85]
	v_mfma_f32_16x16x32_bf16 v[78:81], v[232:235], v[216:219], v[78:81]
	v_mfma_f32_16x16x32_bf16 v[74:77], v[240:243], v[216:219], v[74:77]
	v_mfma_f32_16x16x32_bf16 v[70:73], v[232:235], v[224:227], v[70:73]
	v_mfma_f32_16x16x32_bf16 v[66:69], v[240:243], v[224:227], v[66:69]
	v_readfirstlane_b32 s4, v161
	v_lshl_add_u64 v[250:251], v[196:197], 0, s[58:59]
	s_mov_b32 m0, s4
	v_readfirstlane_b32 s4, v162
	s_barrier
	ds_read_b128 v[192:195], v168 offset:16384
	ds_read_b128 v[200:203], v168 offset:17408
	ds_read_b128 v[204:207], v169 offset:16384
	ds_read_b128 v[208:211], v169 offset:17408
	ds_read_b128 v[212:215], v170 offset:16384
	ds_read_b128 v[216:219], v170 offset:17408
	ds_read_b128 v[220:223], v171 offset:16384
	ds_read_b128 v[224:227], v171 offset:17408
	global_load_lds_dwordx4 v[250:251], off
	v_lshl_add_u64 v[250:251], v[244:245], 0, s[58:59]
	s_mov_b32 m0, s4
	s_nop 0
	global_load_lds_dwordx4 v[250:251], off
	s_barrier
	s_waitcnt lgkmcnt(0)
	v_mfma_f32_16x16x32_bf16 v[62:65], v[176:179], v[192:195], v[62:65]
	v_mfma_f32_16x16x32_bf16 v[58:61], v[184:187], v[192:195], v[58:61]
	v_mfma_f32_16x16x32_bf16 v[54:57], v[176:179], v[204:207], v[54:57]
	v_mfma_f32_16x16x32_bf16 v[50:53], v[184:187], v[204:207], v[50:53]
	v_mfma_f32_16x16x32_bf16 v[46:49], v[176:179], v[212:215], v[46:49]
	v_mfma_f32_16x16x32_bf16 v[42:45], v[184:187], v[212:215], v[42:45]
	v_mfma_f32_16x16x32_bf16 v[38:41], v[176:179], v[220:223], v[38:41]
	v_mfma_f32_16x16x32_bf16 v[34:37], v[184:187], v[220:223], v[34:37]
	v_mfma_f32_16x16x32_bf16 v[62:65], v[180:183], v[200:203], v[62:65]
	v_mfma_f32_16x16x32_bf16 v[58:61], v[188:191], v[200:203], v[58:61]
	v_mfma_f32_16x16x32_bf16 v[54:57], v[180:183], v[208:211], v[54:57]
	v_mfma_f32_16x16x32_bf16 v[50:53], v[188:191], v[208:211], v[50:53]
	v_mfma_f32_16x16x32_bf16 v[46:49], v[180:183], v[216:219], v[46:49]
	v_mfma_f32_16x16x32_bf16 v[42:45], v[188:191], v[216:219], v[42:45]
	v_mfma_f32_16x16x32_bf16 v[38:41], v[180:183], v[224:227], v[38:41]
	v_mfma_f32_16x16x32_bf16 v[34:37], v[188:191], v[224:227], v[34:37]
	s_barrier
	v_readfirstlane_b32 s4, v163
	v_lshl_add_u64 v[176:177], v[246:247], 0, s[60:61]
	s_mov_b32 m0, s4
	v_readfirstlane_b32 s4, v164
	global_load_lds_dwordx4 v[176:177], off
	v_lshl_add_u64 v[176:177], v[248:249], 0, s[60:61]
	s_mov_b32 m0, s4
	s_nop 0
	global_load_lds_dwordx4 v[176:177], off
	s_waitcnt vmcnt(6)
	s_barrier
	v_mfma_f32_16x16x32_bf16 v[30:33], v[228:231], v[192:195], v[30:33]
	v_mfma_f32_16x16x32_bf16 v[26:29], v[236:239], v[192:195], v[26:29]
	v_mfma_f32_16x16x32_bf16 v[22:25], v[228:231], v[204:207], v[22:25]
	v_mfma_f32_16x16x32_bf16 v[18:21], v[236:239], v[204:207], v[18:21]
	v_mfma_f32_16x16x32_bf16 v[14:17], v[228:231], v[212:215], v[14:17]
	v_mfma_f32_16x16x32_bf16 v[10:13], v[236:239], v[212:215], v[10:13]
	v_mfma_f32_16x16x32_bf16 v[6:9], v[228:231], v[220:223], v[6:9]
	v_mfma_f32_16x16x32_bf16 v[2:5], v[236:239], v[220:223], v[2:5]
	v_mfma_f32_16x16x32_bf16 v[30:33], v[232:235], v[200:203], v[30:33]
	v_mfma_f32_16x16x32_bf16 v[26:29], v[240:243], v[200:203], v[26:29]
	v_mfma_f32_16x16x32_bf16 v[22:25], v[232:235], v[208:211], v[22:25]
	v_mfma_f32_16x16x32_bf16 v[18:21], v[240:243], v[208:211], v[18:21]
	v_mfma_f32_16x16x32_bf16 v[14:17], v[232:235], v[216:219], v[14:17]
	v_mfma_f32_16x16x32_bf16 v[10:13], v[240:243], v[216:219], v[10:13]
	v_mfma_f32_16x16x32_bf16 v[6:9], v[232:235], v[224:227], v[6:9]
	v_mfma_f32_16x16x32_bf16 v[2:5], v[240:243], v[224:227], v[2:5]
	s_barrier
	ds_read_b128 v[176:179], v173
	ds_read_b128 v[180:183], v173 offset:1024
	ds_read_b128 v[184:187], v173 offset:2048
	ds_read_b128 v[188:191], v173 offset:3072
	v_readfirstlane_b32 s4, v165
	v_lshl_add_u64 v[228:229], v[196:197], 0, s[62:63]
	s_mov_b32 m0, s4
	v_readfirstlane_b32 s4, v166
	ds_read_b128 v[192:195], v168 offset:32768
	ds_read_b128 v[200:203], v168 offset:33792
	ds_read_b128 v[204:207], v169 offset:32768
	ds_read_b128 v[208:211], v169 offset:33792
	ds_read_b128 v[212:215], v170 offset:32768
	ds_read_b128 v[216:219], v170 offset:33792
	ds_read_b128 v[220:223], v171 offset:32768
	ds_read_b128 v[224:227], v171 offset:33792
	global_load_lds_dwordx4 v[228:229], off
	v_lshl_add_u64 v[228:229], v[244:245], 0, s[62:63]
	s_mov_b32 m0, s4
	s_nop 0
	global_load_lds_dwordx4 v[228:229], off
	s_waitcnt lgkmcnt(8)
	s_barrier
	s_waitcnt lgkmcnt(0)
	v_mfma_f32_16x16x32_bf16 v[126:129], v[176:179], v[192:195], v[126:129]
	v_mfma_f32_16x16x32_bf16 v[122:125], v[184:187], v[192:195], v[122:125]
	v_mfma_f32_16x16x32_bf16 v[118:121], v[176:179], v[204:207], v[118:121]
	v_mfma_f32_16x16x32_bf16 v[114:117], v[184:187], v[204:207], v[114:117]
	v_mfma_f32_16x16x32_bf16 v[110:113], v[176:179], v[212:215], v[110:113]
	v_mfma_f32_16x16x32_bf16 v[106:109], v[184:187], v[212:215], v[106:109]
	v_mfma_f32_16x16x32_bf16 v[102:105], v[176:179], v[220:223], v[102:105]
	v_mfma_f32_16x16x32_bf16 v[98:101], v[184:187], v[220:223], v[98:101]
	v_mfma_f32_16x16x32_bf16 v[126:129], v[180:183], v[200:203], v[126:129]
	v_mfma_f32_16x16x32_bf16 v[122:125], v[188:191], v[200:203], v[122:125]
	v_mfma_f32_16x16x32_bf16 v[118:121], v[180:183], v[208:211], v[118:121]
	v_mfma_f32_16x16x32_bf16 v[114:117], v[188:191], v[208:211], v[114:117]
	v_mfma_f32_16x16x32_bf16 v[110:113], v[180:183], v[216:219], v[110:113]
	v_mfma_f32_16x16x32_bf16 v[106:109], v[188:191], v[216:219], v[106:109]
	v_mfma_f32_16x16x32_bf16 v[102:105], v[180:183], v[224:227], v[102:105]
	v_mfma_f32_16x16x32_bf16 v[98:101], v[188:191], v[224:227], v[98:101]
	s_barrier
	v_readfirstlane_b32 s4, v134
	v_lshl_add_u64 v[250:251], v[246:247], 0, s[66:67]
	s_mov_b32 m0, s4
	v_readfirstlane_b32 s4, v152
	ds_read_b128 v[228:231], v174
	ds_read_b128 v[232:235], v174 offset:1024
	ds_read_b128 v[236:239], v174 offset:2048
	ds_read_b128 v[240:243], v174 offset:3072
	global_load_lds_dwordx4 v[250:251], off
	v_lshl_add_u64 v[250:251], v[248:249], 0, s[66:67]
	s_mov_b32 m0, s4
	s_nop 0
	global_load_lds_dwordx4 v[250:251], off
	s_barrier
	s_waitcnt lgkmcnt(0)
	v_mfma_f32_16x16x32_bf16 v[94:97], v[228:231], v[192:195], v[94:97]
	v_mfma_f32_16x16x32_bf16 v[90:93], v[236:239], v[192:195], v[90:93]
	v_mfma_f32_16x16x32_bf16 v[86:89], v[228:231], v[204:207], v[86:89]
	v_mfma_f32_16x16x32_bf16 v[82:85], v[236:239], v[204:207], v[82:85]
	v_mfma_f32_16x16x32_bf16 v[78:81], v[228:231], v[212:215], v[78:81]
	v_mfma_f32_16x16x32_bf16 v[74:77], v[236:239], v[212:215], v[74:77]
	v_mfma_f32_16x16x32_bf16 v[70:73], v[228:231], v[220:223], v[70:73]
	v_mfma_f32_16x16x32_bf16 v[66:69], v[236:239], v[220:223], v[66:69]
	v_mfma_f32_16x16x32_bf16 v[94:97], v[232:235], v[200:203], v[94:97]
	v_mfma_f32_16x16x32_bf16 v[90:93], v[240:243], v[200:203], v[90:93]
	v_mfma_f32_16x16x32_bf16 v[86:89], v[232:235], v[208:211], v[86:89]
	v_mfma_f32_16x16x32_bf16 v[82:85], v[240:243], v[208:211], v[82:85]
	v_mfma_f32_16x16x32_bf16 v[78:81], v[232:235], v[216:219], v[78:81]
	v_mfma_f32_16x16x32_bf16 v[74:77], v[240:243], v[216:219], v[74:77]
	v_mfma_f32_16x16x32_bf16 v[70:73], v[232:235], v[224:227], v[70:73]
	v_mfma_f32_16x16x32_bf16 v[66:69], v[240:243], v[224:227], v[66:69]
	v_readfirstlane_b32 s4, v153
	v_lshl_add_u64 v[196:197], v[196:197], 0, s[68:69]
	s_mov_b32 m0, s4
	v_readfirstlane_b32 s4, v154
	s_barrier
	ds_read_b128 v[192:195], v168 offset:49152
	ds_read_b128 v[200:203], v168 offset:50176
	ds_read_b128 v[204:207], v169 offset:49152
	ds_read_b128 v[208:211], v169 offset:50176
	ds_read_b128 v[212:215], v170 offset:49152
	ds_read_b128 v[216:219], v170 offset:50176
	ds_read_b128 v[220:223], v171 offset:49152
	ds_read_b128 v[224:227], v171 offset:50176
	global_load_lds_dwordx4 v[196:197], off
	v_lshl_add_u64 v[196:197], v[244:245], 0, s[68:69]
	s_mov_b32 m0, s4
	s_nop 0
	global_load_lds_dwordx4 v[196:197], off
	s_barrier
	s_waitcnt lgkmcnt(0)
	v_mfma_f32_16x16x32_bf16 v[62:65], v[176:179], v[192:195], v[62:65]
	v_mfma_f32_16x16x32_bf16 v[58:61], v[184:187], v[192:195], v[58:61]
	v_mfma_f32_16x16x32_bf16 v[54:57], v[176:179], v[204:207], v[54:57]
	v_mfma_f32_16x16x32_bf16 v[50:53], v[184:187], v[204:207], v[50:53]
	v_mfma_f32_16x16x32_bf16 v[46:49], v[176:179], v[212:215], v[46:49]
	v_mfma_f32_16x16x32_bf16 v[42:45], v[184:187], v[212:215], v[42:45]
	v_mfma_f32_16x16x32_bf16 v[38:41], v[176:179], v[220:223], v[38:41]
	v_mfma_f32_16x16x32_bf16 v[34:37], v[184:187], v[220:223], v[34:37]
	v_mfma_f32_16x16x32_bf16 v[62:65], v[180:183], v[200:203], v[62:65]
	v_mfma_f32_16x16x32_bf16 v[58:61], v[188:191], v[200:203], v[58:61]
	v_mfma_f32_16x16x32_bf16 v[54:57], v[180:183], v[208:211], v[54:57]
	v_mfma_f32_16x16x32_bf16 v[50:53], v[188:191], v[208:211], v[50:53]
	v_mfma_f32_16x16x32_bf16 v[46:49], v[180:183], v[216:219], v[46:49]
	v_mfma_f32_16x16x32_bf16 v[42:45], v[188:191], v[216:219], v[42:45]
	v_mfma_f32_16x16x32_bf16 v[38:41], v[180:183], v[224:227], v[38:41]
	v_mfma_f32_16x16x32_bf16 v[34:37], v[188:191], v[224:227], v[34:37]
	s_barrier
	v_readfirstlane_b32 s4, v155
	v_lshl_add_u64 v[176:177], v[246:247], 0, s[70:71]
	s_mov_b32 m0, s4
	v_readfirstlane_b32 s4, v156
	global_load_lds_dwordx4 v[176:177], off
	v_lshl_add_u64 v[176:177], v[248:249], 0, s[70:71]
	s_mov_b32 m0, s4
	s_nop 0
	global_load_lds_dwordx4 v[176:177], off
	s_waitcnt vmcnt(6)
	s_barrier
	v_mfma_f32_16x16x32_bf16 v[30:33], v[228:231], v[192:195], v[30:33]
	v_mfma_f32_16x16x32_bf16 v[26:29], v[236:239], v[192:195], v[26:29]
	v_mfma_f32_16x16x32_bf16 v[22:25], v[228:231], v[204:207], v[22:25]
	v_mfma_f32_16x16x32_bf16 v[18:21], v[236:239], v[204:207], v[18:21]
	v_mfma_f32_16x16x32_bf16 v[14:17], v[228:231], v[212:215], v[14:17]
	v_mfma_f32_16x16x32_bf16 v[10:13], v[236:239], v[212:215], v[10:13]
	v_mfma_f32_16x16x32_bf16 v[6:9], v[228:231], v[220:223], v[6:9]
	v_mfma_f32_16x16x32_bf16 v[2:5], v[236:239], v[220:223], v[2:5]
	v_mfma_f32_16x16x32_bf16 v[30:33], v[232:235], v[200:203], v[30:33]
	v_mfma_f32_16x16x32_bf16 v[26:29], v[240:243], v[200:203], v[26:29]
	v_mfma_f32_16x16x32_bf16 v[22:25], v[232:235], v[208:211], v[22:25]
	v_mfma_f32_16x16x32_bf16 v[18:21], v[240:243], v[208:211], v[18:21]
	v_mfma_f32_16x16x32_bf16 v[14:17], v[232:235], v[216:219], v[14:17]
	v_mfma_f32_16x16x32_bf16 v[10:13], v[240:243], v[216:219], v[10:13]
	v_mfma_f32_16x16x32_bf16 v[6:9], v[232:235], v[224:227], v[6:9]
	v_mfma_f32_16x16x32_bf16 v[2:5], v[240:243], v[224:227], v[2:5]
	s_add_i32 s1, s1, 2
	s_add_u32 s10, s10, 0x100
	s_addc_u32 s11, s11, 0
	s_cmp_lt_u32 s1, 12
	s_barrier
	s_cbranch_scc1 .LBB0_171
	v_readfirstlane_b32 s1, v157
	v_lshl_add_u64 v[140:141], v[140:141], 0, s[78:79]
	s_mov_b32 m0, s1
	v_readfirstlane_b32 s1, v175
	ds_read_b128 v[144:147], v167
	ds_read_b128 v[148:151], v167 offset:1024
	ds_read_b128 v[152:155], v167 offset:2048
	ds_read_b128 v[176:179], v167 offset:3072
	ds_read_b128 v[180:183], v168
	ds_read_b128 v[184:187], v168 offset:1024
	ds_read_b128 v[188:191], v169
	ds_read_b128 v[192:195], v169 offset:1024
	ds_read_b128 v[200:203], v170
	ds_read_b128 v[204:207], v170 offset:1024
	ds_read_b128 v[208:211], v171
	ds_read_b128 v[212:215], v171 offset:1024
	global_load_lds_dwordx4 v[140:141], off
	v_lshl_add_u64 v[140:141], v[142:143], 0, s[78:79]
	s_mov_b32 m0, s1
	s_nop 0
	global_load_lds_dwordx4 v[140:141], off
	s_barrier
	s_waitcnt lgkmcnt(0)
	v_mfma_f32_16x16x32_bf16 v[126:129], v[144:147], v[180:183], v[126:129]
	v_mfma_f32_16x16x32_bf16 v[122:125], v[152:155], v[180:183], v[122:125]
	v_mfma_f32_16x16x32_bf16 v[118:121], v[144:147], v[188:191], v[118:121]
	v_mfma_f32_16x16x32_bf16 v[114:117], v[152:155], v[188:191], v[114:117]
	v_mfma_f32_16x16x32_bf16 v[102:105], v[144:147], v[208:211], v[102:105]
	v_mfma_f32_16x16x32_bf16 v[98:101], v[152:155], v[208:211], v[98:101]
	v_mfma_f32_16x16x32_bf16 v[126:129], v[148:151], v[184:187], v[126:129]
	v_mfma_f32_16x16x32_bf16 v[122:125], v[176:179], v[184:187], v[122:125]
	v_mfma_f32_16x16x32_bf16 v[118:121], v[148:151], v[192:195], v[118:121]
	v_mfma_f32_16x16x32_bf16 v[114:117], v[176:179], v[192:195], v[114:117]
	v_mfma_f32_16x16x32_bf16 v[110:113], v[144:147], v[200:203], v[110:113]
	v_mfma_f32_16x16x32_bf16 v[106:109], v[152:155], v[200:203], v[106:109]
	v_mfma_f32_16x16x32_bf16 v[102:105], v[148:151], v[212:215], v[102:105]
	v_mfma_f32_16x16x32_bf16 v[98:101], v[176:179], v[212:215], v[98:101]
	v_mfma_f32_16x16x32_bf16 v[140:143], v[148:151], v[204:207], v[110:113]
	v_mfma_f32_16x16x32_bf16 v[216:219], v[176:179], v[204:207], v[106:109]
	s_barrier
	s_nop 1
	ds_read_b128 v[106:109], v172
	ds_read_b128 v[110:113], v172 offset:1024
	ds_read_b128 v[220:223], v172 offset:2048
	ds_read_b128 v[224:227], v172 offset:3072
	s_barrier
	s_waitcnt lgkmcnt(0)
	v_mfma_f32_16x16x32_bf16 v[86:89], v[106:109], v[188:191], v[86:89]
	v_mfma_f32_16x16x32_bf16 v[82:85], v[220:223], v[188:191], v[82:85]
	v_mfma_f32_16x16x32_bf16 v[70:73], v[106:109], v[208:211], v[70:73]
	v_mfma_f32_16x16x32_bf16 v[66:69], v[220:223], v[208:211], v[66:69]
	v_mfma_f32_16x16x32_bf16 v[94:97], v[106:109], v[180:183], v[94:97]
	v_mfma_f32_16x16x32_bf16 v[90:93], v[220:223], v[180:183], v[90:93]
	v_mfma_f32_16x16x32_bf16 v[86:89], v[110:113], v[192:195], v[86:89]
	v_mfma_f32_16x16x32_bf16 v[82:85], v[224:227], v[192:195], v[82:85]
	v_mfma_f32_16x16x32_bf16 v[78:81], v[106:109], v[200:203], v[78:81]
	v_mfma_f32_16x16x32_bf16 v[74:77], v[220:223], v[200:203], v[74:77]
	v_mfma_f32_16x16x32_bf16 v[70:73], v[110:113], v[212:215], v[70:73]
	v_mfma_f32_16x16x32_bf16 v[66:69], v[224:227], v[212:215], v[66:69]
	v_mfma_f32_16x16x32_bf16 v[228:231], v[110:113], v[184:187], v[94:97]
	v_mfma_f32_16x16x32_bf16 v[180:183], v[224:227], v[184:187], v[90:93]
	v_mfma_f32_16x16x32_bf16 v[184:187], v[110:113], v[204:207], v[78:81]
	v_mfma_f32_16x16x32_bf16 v[188:191], v[224:227], v[204:207], v[74:77]
	s_barrier
	s_nop 0
	ds_read_b128 v[74:77], v168 offset:16384
	ds_read_b128 v[78:81], v168 offset:17408
	ds_read_b128 v[90:93], v169 offset:16384
	ds_read_b128 v[94:97], v169 offset:17408
	ds_read_b128 v[192:195], v170 offset:16384
	ds_read_b128 v[200:203], v170 offset:17408
	ds_read_b128 v[204:207], v171 offset:16384
	ds_read_b128 v[208:211], v171 offset:17408
	s_waitcnt vmcnt(4)
	s_barrier
	s_waitcnt lgkmcnt(0)
	v_mfma_f32_16x16x32_bf16 v[62:65], v[144:147], v[74:77], v[62:65]
	v_mfma_f32_16x16x32_bf16 v[58:61], v[152:155], v[74:77], v[58:61]
	v_mfma_f32_16x16x32_bf16 v[54:57], v[144:147], v[90:93], v[54:57]
	v_mfma_f32_16x16x32_bf16 v[50:53], v[152:155], v[90:93], v[50:53]
	v_mfma_f32_16x16x32_bf16 v[38:41], v[144:147], v[204:207], v[38:41]
	v_mfma_f32_16x16x32_bf16 v[34:37], v[152:155], v[204:207], v[34:37]
	v_mfma_f32_16x16x32_bf16 v[62:65], v[148:151], v[78:81], v[62:65]
	v_mfma_f32_16x16x32_bf16 v[58:61], v[176:179], v[78:81], v[58:61]
	v_mfma_f32_16x16x32_bf16 v[54:57], v[148:151], v[94:97], v[54:57]
	v_mfma_f32_16x16x32_bf16 v[50:53], v[176:179], v[94:97], v[50:53]
	v_mfma_f32_16x16x32_bf16 v[46:49], v[144:147], v[192:195], v[46:49]
	v_mfma_f32_16x16x32_bf16 v[42:45], v[152:155], v[192:195], v[42:45]
	v_mfma_f32_16x16x32_bf16 v[38:41], v[148:151], v[208:211], v[38:41]
	v_mfma_f32_16x16x32_bf16 v[34:37], v[176:179], v[208:211], v[34:37]
	v_mfma_f32_16x16x32_bf16 v[212:215], v[148:151], v[200:203], v[46:49]
	v_mfma_f32_16x16x32_bf16 v[232:235], v[176:179], v[200:203], v[42:45]
	v_mfma_f32_16x16x32_bf16 v[22:25], v[106:109], v[90:93], v[22:25]
	v_mfma_f32_16x16x32_bf16 v[18:21], v[220:223], v[90:93], v[18:21]
	v_mfma_f32_16x16x32_bf16 v[6:9], v[106:109], v[204:207], v[6:9]
	v_mfma_f32_16x16x32_bf16 v[2:5], v[220:223], v[204:207], v[2:5]
	v_mfma_f32_16x16x32_bf16 v[30:33], v[106:109], v[74:77], v[30:33]
	v_mfma_f32_16x16x32_bf16 v[26:29], v[220:223], v[74:77], v[26:29]
	v_mfma_f32_16x16x32_bf16 v[22:25], v[110:113], v[94:97], v[22:25]
	v_mfma_f32_16x16x32_bf16 v[18:21], v[224:227], v[94:97], v[18:21]
	v_mfma_f32_16x16x32_bf16 v[14:17], v[106:109], v[192:195], v[14:17]
	v_mfma_f32_16x16x32_bf16 v[10:13], v[220:223], v[192:195], v[10:13]
	v_mfma_f32_16x16x32_bf16 v[6:9], v[110:113], v[208:211], v[6:9]
	v_mfma_f32_16x16x32_bf16 v[2:5], v[224:227], v[208:211], v[2:5]
	v_mfma_f32_16x16x32_bf16 v[144:147], v[110:113], v[78:81], v[30:33]
	v_mfma_f32_16x16x32_bf16 v[148:151], v[224:227], v[78:81], v[26:29]
	v_mfma_f32_16x16x32_bf16 v[152:155], v[110:113], v[200:203], v[14:17]
	v_mfma_f32_16x16x32_bf16 v[176:179], v[224:227], v[200:203], v[10:13]
	s_barrier
	s_nop 0
	ds_read_b128 v[10:13], v173
	ds_read_b128 v[14:17], v173 offset:1024
	ds_read_b128 v[192:195], v173 offset:2048
	ds_read_b128 v[200:203], v173 offset:3072
	ds_read_b128 v[26:29], v168 offset:32768
	ds_read_b128 v[30:33], v168 offset:33792
	ds_read_b128 v[42:45], v169 offset:32768
	ds_read_b128 v[46:49], v169 offset:33792
	ds_read_b128 v[204:207], v170 offset:32768
	ds_read_b128 v[208:211], v170 offset:33792
	ds_read_b128 v[220:223], v171 offset:32768
	ds_read_b128 v[224:227], v171 offset:33792
	s_waitcnt vmcnt(2)
	s_barrier
	s_waitcnt lgkmcnt(0)
	v_mfma_f32_16x16x32_bf16 v[74:77], v[10:13], v[26:29], v[126:129]
	v_mfma_f32_16x16x32_bf16 v[126:129], v[14:17], v[30:33], v[74:77]
	v_mfma_f32_16x16x32_bf16 v[74:77], v[192:195], v[26:29], v[122:125]
	v_mfma_f32_16x16x32_bf16 v[122:125], v[200:203], v[30:33], v[74:77]
	v_mfma_f32_16x16x32_bf16 v[74:77], v[10:13], v[42:45], v[118:121]
	v_mfma_f32_16x16x32_bf16 v[110:113], v[14:17], v[46:49], v[74:77]
	v_mfma_f32_16x16x32_bf16 v[74:77], v[192:195], v[42:45], v[114:117]
	v_mfma_f32_16x16x32_bf16 v[106:109], v[200:203], v[46:49], v[74:77]
	v_mfma_f32_16x16x32_bf16 v[74:77], v[10:13], v[204:207], v[140:143]
	v_mfma_f32_16x16x32_bf16 v[94:97], v[14:17], v[208:211], v[74:77]
	v_mfma_f32_16x16x32_bf16 v[74:77], v[192:195], v[204:207], v[216:219]
	v_mfma_f32_16x16x32_bf16 v[90:93], v[200:203], v[208:211], v[74:77]
	v_mfma_f32_16x16x32_bf16 v[74:77], v[10:13], v[220:223], v[102:105]
	v_mfma_f32_16x16x32_bf16 v[78:81], v[14:17], v[224:227], v[74:77]
	v_mfma_f32_16x16x32_bf16 v[74:77], v[192:195], v[220:223], v[98:101]
	v_mfma_f32_16x16x32_bf16 v[74:77], v[200:203], v[224:227], v[74:77]
	s_barrier
	ds_read_b128 v[140:143], v174
	ds_read_b128 v[216:219], v174 offset:1024
	ds_read_b128 v[236:239], v174 offset:2048
	ds_read_b128 v[240:243], v174 offset:3072
	s_waitcnt vmcnt(0)
	s_barrier
	s_waitcnt lgkmcnt(0)
	v_mfma_f32_16x16x32_bf16 v[98:101], v[140:143], v[26:29], v[228:231]
	v_mfma_f32_16x16x32_bf16 v[26:29], v[236:239], v[26:29], v[180:183]
	v_mfma_f32_16x16x32_bf16 v[114:117], v[240:243], v[30:33], v[26:29]
	v_mfma_f32_16x16x32_bf16 v[26:29], v[140:143], v[42:45], v[86:89]
	v_mfma_f32_16x16x32_bf16 v[102:105], v[216:219], v[46:49], v[26:29]
	v_mfma_f32_16x16x32_bf16 v[26:29], v[236:239], v[42:45], v[82:85]
	v_mfma_f32_16x16x32_bf16 v[118:121], v[216:219], v[30:33], v[98:101]
	v_mfma_f32_16x16x32_bf16 v[98:101], v[240:243], v[46:49], v[26:29]
	v_mfma_f32_16x16x32_bf16 v[26:29], v[140:143], v[204:207], v[184:187]
	v_mfma_f32_16x16x32_bf16 v[86:89], v[216:219], v[208:211], v[26:29]
	v_mfma_f32_16x16x32_bf16 v[26:29], v[236:239], v[204:207], v[188:191]
	v_mfma_f32_16x16x32_bf16 v[82:85], v[240:243], v[208:211], v[26:29]
	v_mfma_f32_16x16x32_bf16 v[26:29], v[140:143], v[220:223], v[70:73]
	v_mfma_f32_16x16x32_bf16 v[70:73], v[216:219], v[224:227], v[26:29]
	v_mfma_f32_16x16x32_bf16 v[26:29], v[236:239], v[220:223], v[66:69]
	v_mfma_f32_16x16x32_bf16 v[66:69], v[240:243], v[224:227], v[26:29]
	s_barrier
	ds_read_b128 v[180:183], v168 offset:49152
	ds_read_b128 v[184:187], v168 offset:50176
	ds_read_b128 v[188:191], v169 offset:49152
	ds_read_b128 v[204:207], v169 offset:50176
	ds_read_b128 v[208:211], v170 offset:49152
	ds_read_b128 v[220:223], v170 offset:50176
	ds_read_b128 v[224:227], v171 offset:49152
	ds_read_b128 v[228:231], v171 offset:50176
	s_barrier
	s_waitcnt lgkmcnt(0)
	v_mfma_f32_16x16x32_bf16 v[26:29], v[10:13], v[180:183], v[62:65]
	v_mfma_f32_16x16x32_bf16 v[62:65], v[14:17], v[184:187], v[26:29]
	v_mfma_f32_16x16x32_bf16 v[26:29], v[192:195], v[180:183], v[58:61]
	v_mfma_f32_16x16x32_bf16 v[58:61], v[200:203], v[184:187], v[26:29]
	v_mfma_f32_16x16x32_bf16 v[26:29], v[10:13], v[188:191], v[54:57]
	v_mfma_f32_16x16x32_bf16 v[46:49], v[14:17], v[204:207], v[26:29]
	v_mfma_f32_16x16x32_bf16 v[26:29], v[192:195], v[188:191], v[50:53]
	v_mfma_f32_16x16x32_bf16 v[42:45], v[200:203], v[204:207], v[26:29]
	v_mfma_f32_16x16x32_bf16 v[26:29], v[10:13], v[208:211], v[212:215]
	v_mfma_f32_16x16x32_bf16 v[10:13], v[10:13], v[224:227], v[38:41]
	v_mfma_f32_16x16x32_bf16 v[30:33], v[14:17], v[220:223], v[26:29]
	v_mfma_f32_16x16x32_bf16 v[26:29], v[192:195], v[208:211], v[232:235]
	v_mfma_f32_16x16x32_bf16 v[14:17], v[14:17], v[228:231], v[10:13]
	v_mfma_f32_16x16x32_bf16 v[10:13], v[192:195], v[224:227], v[34:37]
	v_mfma_f32_16x16x32_bf16 v[26:29], v[200:203], v[220:223], v[26:29]
	v_mfma_f32_16x16x32_bf16 v[10:13], v[200:203], v[228:231], v[10:13]
	v_mfma_f32_16x16x32_bf16 v[34:37], v[140:143], v[180:183], v[144:147]
	v_mfma_f32_16x16x32_bf16 v[54:57], v[216:219], v[184:187], v[34:37]
	v_mfma_f32_16x16x32_bf16 v[34:37], v[236:239], v[180:183], v[148:151]
	v_mfma_f32_16x16x32_bf16 v[18:21], v[236:239], v[188:191], v[18:21]
	v_mfma_f32_16x16x32_bf16 v[50:53], v[240:243], v[184:187], v[34:37]
	v_mfma_f32_16x16x32_bf16 v[22:25], v[140:143], v[188:191], v[22:25]
	v_mfma_f32_16x16x32_bf16 v[34:37], v[240:243], v[204:207], v[18:21]
	v_mfma_f32_16x16x32_bf16 v[18:21], v[140:143], v[208:211], v[152:155]
	v_mfma_f32_16x16x32_bf16 v[38:41], v[216:219], v[204:207], v[22:25]
	v_mfma_f32_16x16x32_bf16 v[22:25], v[216:219], v[220:223], v[18:21]
	v_mfma_f32_16x16x32_bf16 v[18:21], v[236:239], v[208:211], v[176:179]
	v_mfma_f32_16x16x32_bf16 v[6:9], v[140:143], v[224:227], v[6:9]
	v_mfma_f32_16x16x32_bf16 v[2:5], v[236:239], v[224:227], v[2:5]
	v_mfma_f32_16x16x32_bf16 v[18:21], v[240:243], v[220:223], v[18:21]
	v_mfma_f32_16x16x32_bf16 v[6:9], v[216:219], v[228:231], v[6:9]
	v_mfma_f32_16x16x32_bf16 v[2:5], v[240:243], v[228:231], v[2:5]
	s_barrier
	s_and_saveexec_b64 s[4:5], s[74:75]
	s_cbranch_execz .LBB0_174
	s_barrier

.LBB0_2247:
	ds_read_b128 v[178:181], v162
	ds_read_b128 v[182:185], v162 offset:1024
	ds_read_b128 v[186:189], v162 offset:2048
	ds_read_b128 v[190:193], v162 offset:3072
	v_add_u32_e32 v175, 0xc000, v155
	v_lshl_add_u64 v[244:245], s[36:37], 0, v[148:149]
	v_readfirstlane_b32 s35, v175
	v_lshl_add_u64 v[176:177], v[244:245], 0, s[14:15]
	s_mov_b32 m0, s35
	ds_read_b128 v[194:197], v163
	ds_read_b128 v[200:203], v163 offset:1024
	ds_read_b128 v[204:207], v164
	ds_read_b128 v[208:211], v164 offset:1024
	ds_read_b128 v[212:215], v165
	ds_read_b128 v[216:219], v165 offset:1024
	ds_read_b128 v[220:223], v166
	ds_read_b128 v[224:227], v166 offset:1024
	global_load_lds_dwordx4 v[176:177], off
	v_add_u32_e32 v176, 0xe000, v155
	v_lshl_add_u64 v[246:247], s[36:37], 0, v[150:151]
	v_readfirstlane_b32 s35, v176
	v_lshl_add_u64 v[228:229], v[246:247], 0, s[14:15]
	s_mov_b32 m0, s35
	s_nop 0
	global_load_lds_dwordx4 v[228:229], off
	s_waitcnt lgkmcnt(8)
	s_barrier
	s_waitcnt lgkmcnt(0)
	v_mfma_f32_16x16x32_bf16 v[126:129], v[178:181], v[194:197], v[126:129]
	v_mfma_f32_16x16x32_bf16 v[122:125], v[186:189], v[194:197], v[122:125]
	v_mfma_f32_16x16x32_bf16 v[118:121], v[178:181], v[204:207], v[118:121]
	v_mfma_f32_16x16x32_bf16 v[114:117], v[186:189], v[204:207], v[114:117]
	v_mfma_f32_16x16x32_bf16 v[110:113], v[178:181], v[212:215], v[110:113]
	v_mfma_f32_16x16x32_bf16 v[106:109], v[186:189], v[212:215], v[106:109]
	v_mfma_f32_16x16x32_bf16 v[102:105], v[178:181], v[220:223], v[102:105]
	v_mfma_f32_16x16x32_bf16 v[98:101], v[186:189], v[220:223], v[98:101]
	v_mfma_f32_16x16x32_bf16 v[126:129], v[182:185], v[200:203], v[126:129]
	v_mfma_f32_16x16x32_bf16 v[122:125], v[190:193], v[200:203], v[122:125]
	v_mfma_f32_16x16x32_bf16 v[118:121], v[182:185], v[208:211], v[118:121]
	v_mfma_f32_16x16x32_bf16 v[114:117], v[190:193], v[208:211], v[114:117]
	v_mfma_f32_16x16x32_bf16 v[110:113], v[182:185], v[216:219], v[110:113]
	v_mfma_f32_16x16x32_bf16 v[106:109], v[190:193], v[216:219], v[106:109]
	v_mfma_f32_16x16x32_bf16 v[102:105], v[182:185], v[224:227], v[102:105]
	v_mfma_f32_16x16x32_bf16 v[98:101], v[190:193], v[224:227], v[98:101]
	s_barrier
	v_lshl_add_u64 v[248:249], s[36:37], 0, v[144:145]
	v_readfirstlane_b32 s35, v153
	v_lshl_add_u64 v[250:251], v[248:249], 0, s[16:17]
	s_mov_b32 m0, s35
	ds_read_b128 v[228:231], v167
	ds_read_b128 v[232:235], v167 offset:1024
	ds_read_b128 v[236:239], v167 offset:2048
	ds_read_b128 v[240:243], v167 offset:3072
	global_load_lds_dwordx4 v[250:251], off
	v_lshl_add_u64 v[250:251], s[36:37], 0, v[146:147]
	v_readfirstlane_b32 s35, v154
	v_lshl_add_u64 v[252:253], v[250:251], 0, s[16:17]
	s_mov_b32 m0, s35
	s_nop 0
	global_load_lds_dwordx4 v[252:253], off
	s_barrier
	s_waitcnt lgkmcnt(0)
	v_mfma_f32_16x16x32_bf16 v[94:97], v[228:231], v[194:197], v[94:97]
	v_mfma_f32_16x16x32_bf16 v[90:93], v[236:239], v[194:197], v[90:93]
	v_mfma_f32_16x16x32_bf16 v[86:89], v[228:231], v[204:207], v[86:89]
	v_mfma_f32_16x16x32_bf16 v[82:85], v[236:239], v[204:207], v[82:85]
	v_mfma_f32_16x16x32_bf16 v[78:81], v[228:231], v[212:215], v[78:81]
	v_mfma_f32_16x16x32_bf16 v[74:77], v[236:239], v[212:215], v[74:77]
	v_mfma_f32_16x16x32_bf16 v[70:73], v[228:231], v[220:223], v[70:73]
	v_mfma_f32_16x16x32_bf16 v[66:69], v[236:239], v[220:223], v[66:69]
	v_mfma_f32_16x16x32_bf16 v[94:97], v[232:235], v[200:203], v[94:97]
	v_mfma_f32_16x16x32_bf16 v[90:93], v[240:243], v[200:203], v[90:93]
	v_mfma_f32_16x16x32_bf16 v[86:89], v[232:235], v[208:211], v[86:89]
	v_mfma_f32_16x16x32_bf16 v[82:85], v[240:243], v[208:211], v[82:85]
	v_mfma_f32_16x16x32_bf16 v[78:81], v[232:235], v[216:219], v[78:81]
	v_mfma_f32_16x16x32_bf16 v[74:77], v[240:243], v[216:219], v[74:77]
	v_mfma_f32_16x16x32_bf16 v[70:73], v[232:235], v[224:227], v[70:73]
	v_mfma_f32_16x16x32_bf16 v[66:69], v[240:243], v[224:227], v[66:69]
	v_readfirstlane_b32 s35, v155
	v_lshl_add_u64 v[252:253], v[244:245], 0, s[18:19]
	s_mov_b32 m0, s35
	v_readfirstlane_b32 s35, v156
	s_barrier
	ds_read_b128 v[194:197], v163 offset:16384
	ds_read_b128 v[200:203], v163 offset:17408
	ds_read_b128 v[204:207], v164 offset:16384
	ds_read_b128 v[208:211], v164 offset:17408
	ds_read_b128 v[212:215], v165 offset:16384
	ds_read_b128 v[216:219], v165 offset:17408
	ds_read_b128 v[220:223], v166 offset:16384
	ds_read_b128 v[224:227], v166 offset:17408
	global_load_lds_dwordx4 v[252:253], off
	v_lshl_add_u64 v[252:253], v[246:247], 0, s[18:19]
	s_mov_b32 m0, s35
	s_nop 0
	global_load_lds_dwordx4 v[252:253], off
	s_barrier
	s_waitcnt lgkmcnt(0)
	v_mfma_f32_16x16x32_bf16 v[62:65], v[178:181], v[194:197], v[62:65]
	v_mfma_f32_16x16x32_bf16 v[58:61], v[186:189], v[194:197], v[58:61]
	v_mfma_f32_16x16x32_bf16 v[54:57], v[178:181], v[204:207], v[54:57]
	v_mfma_f32_16x16x32_bf16 v[50:53], v[186:189], v[204:207], v[50:53]
	v_mfma_f32_16x16x32_bf16 v[46:49], v[178:181], v[212:215], v[46:49]
	v_mfma_f32_16x16x32_bf16 v[42:45], v[186:189], v[212:215], v[42:45]
	v_mfma_f32_16x16x32_bf16 v[38:41], v[178:181], v[220:223], v[38:41]
	v_mfma_f32_16x16x32_bf16 v[34:37], v[186:189], v[220:223], v[34:37]
	v_mfma_f32_16x16x32_bf16 v[62:65], v[182:185], v[200:203], v[62:65]
	v_mfma_f32_16x16x32_bf16 v[58:61], v[190:193], v[200:203], v[58:61]
	v_mfma_f32_16x16x32_bf16 v[54:57], v[182:185], v[208:211], v[54:57]
	v_mfma_f32_16x16x32_bf16 v[50:53], v[190:193], v[208:211], v[50:53]
	v_mfma_f32_16x16x32_bf16 v[46:49], v[182:185], v[216:219], v[46:49]
	v_mfma_f32_16x16x32_bf16 v[42:45], v[190:193], v[216:219], v[42:45]
	v_mfma_f32_16x16x32_bf16 v[38:41], v[182:185], v[224:227], v[38:41]
	v_mfma_f32_16x16x32_bf16 v[34:37], v[190:193], v[224:227], v[34:37]
	s_barrier
	v_readfirstlane_b32 s35, v157
	v_lshl_add_u64 v[178:179], v[248:249], 0, s[20:21]
	s_mov_b32 m0, s35
	v_readfirstlane_b32 s35, v158
	global_load_lds_dwordx4 v[178:179], off
	v_lshl_add_u64 v[178:179], v[250:251], 0, s[20:21]
	s_mov_b32 m0, s35
	s_nop 0
	global_load_lds_dwordx4 v[178:179], off
	s_waitcnt vmcnt(6)
	s_barrier
	v_mfma_f32_16x16x32_bf16 v[30:33], v[228:231], v[194:197], v[30:33]
	v_mfma_f32_16x16x32_bf16 v[26:29], v[236:239], v[194:197], v[26:29]
	v_mfma_f32_16x16x32_bf16 v[22:25], v[228:231], v[204:207], v[22:25]
	v_mfma_f32_16x16x32_bf16 v[18:21], v[236:239], v[204:207], v[18:21]
	v_mfma_f32_16x16x32_bf16 v[14:17], v[228:231], v[212:215], v[14:17]
	v_mfma_f32_16x16x32_bf16 v[10:13], v[236:239], v[212:215], v[10:13]
	v_mfma_f32_16x16x32_bf16 v[6:9], v[228:231], v[220:223], v[6:9]
	v_mfma_f32_16x16x32_bf16 v[2:5], v[236:239], v[220:223], v[2:5]
	v_mfma_f32_16x16x32_bf16 v[30:33], v[232:235], v[200:203], v[30:33]
	v_mfma_f32_16x16x32_bf16 v[26:29], v[240:243], v[200:203], v[26:29]
	v_mfma_f32_16x16x32_bf16 v[22:25], v[232:235], v[208:211], v[22:25]
	v_mfma_f32_16x16x32_bf16 v[18:21], v[240:243], v[208:211], v[18:21]
	v_mfma_f32_16x16x32_bf16 v[14:17], v[232:235], v[216:219], v[14:17]
	v_mfma_f32_16x16x32_bf16 v[10:13], v[240:243], v[216:219], v[10:13]
	v_mfma_f32_16x16x32_bf16 v[6:9], v[232:235], v[224:227], v[6:9]
	v_mfma_f32_16x16x32_bf16 v[2:5], v[240:243], v[224:227], v[2:5]
	s_barrier
	ds_read_b128 v[178:181], v168
	ds_read_b128 v[182:185], v168 offset:1024
	ds_read_b128 v[186:189], v168 offset:2048
	ds_read_b128 v[190:193], v168 offset:3072
	v_readfirstlane_b32 s35, v159
	v_lshl_add_u64 v[228:229], v[244:245], 0, s[22:23]
	s_mov_b32 m0, s35
	v_readfirstlane_b32 s35, v160
	ds_read_b128 v[194:197], v163 offset:32768
	ds_read_b128 v[200:203], v163 offset:33792
	ds_read_b128 v[204:207], v164 offset:32768
	ds_read_b128 v[208:211], v164 offset:33792
	ds_read_b128 v[212:215], v165 offset:32768
	ds_read_b128 v[216:219], v165 offset:33792
	ds_read_b128 v[220:223], v166 offset:32768
	ds_read_b128 v[224:227], v166 offset:33792
	global_load_lds_dwordx4 v[228:229], off
	v_lshl_add_u64 v[228:229], v[246:247], 0, s[22:23]
	s_mov_b32 m0, s35
	s_nop 0
	global_load_lds_dwordx4 v[228:229], off
	s_waitcnt lgkmcnt(8)
	s_barrier
	s_waitcnt lgkmcnt(0)
	v_mfma_f32_16x16x32_bf16 v[126:129], v[178:181], v[194:197], v[126:129]
	v_mfma_f32_16x16x32_bf16 v[122:125], v[186:189], v[194:197], v[122:125]
	v_mfma_f32_16x16x32_bf16 v[118:121], v[178:181], v[204:207], v[118:121]
	v_mfma_f32_16x16x32_bf16 v[114:117], v[186:189], v[204:207], v[114:117]
	v_mfma_f32_16x16x32_bf16 v[110:113], v[178:181], v[212:215], v[110:113]
	v_mfma_f32_16x16x32_bf16 v[106:109], v[186:189], v[212:215], v[106:109]
	v_mfma_f32_16x16x32_bf16 v[102:105], v[178:181], v[220:223], v[102:105]
	v_mfma_f32_16x16x32_bf16 v[98:101], v[186:189], v[220:223], v[98:101]
	v_mfma_f32_16x16x32_bf16 v[126:129], v[182:185], v[200:203], v[126:129]
	v_mfma_f32_16x16x32_bf16 v[122:125], v[190:193], v[200:203], v[122:125]
	v_mfma_f32_16x16x32_bf16 v[118:121], v[182:185], v[208:211], v[118:121]
	v_mfma_f32_16x16x32_bf16 v[114:117], v[190:193], v[208:211], v[114:117]
	v_mfma_f32_16x16x32_bf16 v[110:113], v[182:185], v[216:219], v[110:113]
	v_mfma_f32_16x16x32_bf16 v[106:109], v[190:193], v[216:219], v[106:109]
	v_mfma_f32_16x16x32_bf16 v[102:105], v[182:185], v[224:227], v[102:105]
	v_mfma_f32_16x16x32_bf16 v[98:101], v[190:193], v[224:227], v[98:101]
	s_barrier
	v_readfirstlane_b32 s35, v134
	v_lshl_add_u64 v[252:253], v[248:249], 0, s[24:25]
	s_mov_b32 m0, s35
	v_readfirstlane_b32 s35, v170
	ds_read_b128 v[228:231], v169
	ds_read_b128 v[232:235], v169 offset:1024
	ds_read_b128 v[236:239], v169 offset:2048
	ds_read_b128 v[240:243], v169 offset:3072
	global_load_lds_dwordx4 v[252:253], off
	v_lshl_add_u64 v[252:253], v[250:251], 0, s[24:25]
	s_mov_b32 m0, s35
	s_nop 0
	global_load_lds_dwordx4 v[252:253], off
	s_barrier
	s_waitcnt lgkmcnt(0)
	v_mfma_f32_16x16x32_bf16 v[94:97], v[228:231], v[194:197], v[94:97]
	v_mfma_f32_16x16x32_bf16 v[90:93], v[236:239], v[194:197], v[90:93]
	v_mfma_f32_16x16x32_bf16 v[86:89], v[228:231], v[204:207], v[86:89]
	v_mfma_f32_16x16x32_bf16 v[82:85], v[236:239], v[204:207], v[82:85]
	v_mfma_f32_16x16x32_bf16 v[78:81], v[228:231], v[212:215], v[78:81]
	v_mfma_f32_16x16x32_bf16 v[74:77], v[236:239], v[212:215], v[74:77]
	v_mfma_f32_16x16x32_bf16 v[70:73], v[228:231], v[220:223], v[70:73]
	v_mfma_f32_16x16x32_bf16 v[66:69], v[236:239], v[220:223], v[66:69]
	v_mfma_f32_16x16x32_bf16 v[94:97], v[232:235], v[200:203], v[94:97]
	v_mfma_f32_16x16x32_bf16 v[90:93], v[240:243], v[200:203], v[90:93]
	v_mfma_f32_16x16x32_bf16 v[86:89], v[232:235], v[208:211], v[86:89]
	v_mfma_f32_16x16x32_bf16 v[82:85], v[240:243], v[208:211], v[82:85]
	v_mfma_f32_16x16x32_bf16 v[78:81], v[232:235], v[216:219], v[78:81]
	v_mfma_f32_16x16x32_bf16 v[74:77], v[240:243], v[216:219], v[74:77]
	v_mfma_f32_16x16x32_bf16 v[70:73], v[232:235], v[224:227], v[70:73]
	v_mfma_f32_16x16x32_bf16 v[66:69], v[240:243], v[224:227], v[66:69]
	v_readfirstlane_b32 s35, v171
	v_lshl_add_u64 v[244:245], v[244:245], 0, s[26:27]
	s_mov_b32 m0, s35
	v_readfirstlane_b32 s35, v172
	s_barrier
	ds_read_b128 v[194:197], v163 offset:49152
	ds_read_b128 v[200:203], v163 offset:50176
	ds_read_b128 v[204:207], v164 offset:49152
	ds_read_b128 v[208:211], v164 offset:50176
	ds_read_b128 v[212:215], v165 offset:49152
	ds_read_b128 v[216:219], v165 offset:50176
	ds_read_b128 v[220:223], v166 offset:49152
	ds_read_b128 v[224:227], v166 offset:50176
	global_load_lds_dwordx4 v[244:245], off
	v_lshl_add_u64 v[244:245], v[246:247], 0, s[26:27]
	s_mov_b32 m0, s35
	s_nop 0
	global_load_lds_dwordx4 v[244:245], off
	s_barrier
	s_waitcnt lgkmcnt(0)
	v_mfma_f32_16x16x32_bf16 v[62:65], v[178:181], v[194:197], v[62:65]
	v_mfma_f32_16x16x32_bf16 v[58:61], v[186:189], v[194:197], v[58:61]
	v_mfma_f32_16x16x32_bf16 v[54:57], v[178:181], v[204:207], v[54:57]
	v_mfma_f32_16x16x32_bf16 v[50:53], v[186:189], v[204:207], v[50:53]
	v_mfma_f32_16x16x32_bf16 v[46:49], v[178:181], v[212:215], v[46:49]
	v_mfma_f32_16x16x32_bf16 v[42:45], v[186:189], v[212:215], v[42:45]
	v_mfma_f32_16x16x32_bf16 v[38:41], v[178:181], v[220:223], v[38:41]
	v_mfma_f32_16x16x32_bf16 v[34:37], v[186:189], v[220:223], v[34:37]
	v_mfma_f32_16x16x32_bf16 v[62:65], v[182:185], v[200:203], v[62:65]
	v_mfma_f32_16x16x32_bf16 v[58:61], v[190:193], v[200:203], v[58:61]
	v_mfma_f32_16x16x32_bf16 v[54:57], v[182:185], v[208:211], v[54:57]
	v_mfma_f32_16x16x32_bf16 v[50:53], v[190:193], v[208:211], v[50:53]
	v_mfma_f32_16x16x32_bf16 v[46:49], v[182:185], v[216:219], v[46:49]
	v_mfma_f32_16x16x32_bf16 v[42:45], v[190:193], v[216:219], v[42:45]
	v_mfma_f32_16x16x32_bf16 v[38:41], v[182:185], v[224:227], v[38:41]
	v_mfma_f32_16x16x32_bf16 v[34:37], v[190:193], v[224:227], v[34:37]
	s_barrier
	v_readfirstlane_b32 s35, v173
	v_lshl_add_u64 v[178:179], v[248:249], 0, s[28:29]
	s_mov_b32 m0, s35
	v_readfirstlane_b32 s35, v174
	global_load_lds_dwordx4 v[178:179], off
	v_lshl_add_u64 v[178:179], v[250:251], 0, s[28:29]
	s_mov_b32 m0, s35
	s_nop 0
	global_load_lds_dwordx4 v[178:179], off
	s_waitcnt vmcnt(6)
	s_barrier
	v_mfma_f32_16x16x32_bf16 v[30:33], v[228:231], v[194:197], v[30:33]
	v_mfma_f32_16x16x32_bf16 v[26:29], v[236:239], v[194:197], v[26:29]
	v_mfma_f32_16x16x32_bf16 v[22:25], v[228:231], v[204:207], v[22:25]
	v_mfma_f32_16x16x32_bf16 v[18:21], v[236:239], v[204:207], v[18:21]
	v_mfma_f32_16x16x32_bf16 v[14:17], v[228:231], v[212:215], v[14:17]
	v_mfma_f32_16x16x32_bf16 v[10:13], v[236:239], v[212:215], v[10:13]
	v_mfma_f32_16x16x32_bf16 v[6:9], v[228:231], v[220:223], v[6:9]
	v_mfma_f32_16x16x32_bf16 v[2:5], v[236:239], v[220:223], v[2:5]
	v_mfma_f32_16x16x32_bf16 v[30:33], v[232:235], v[200:203], v[30:33]
	v_mfma_f32_16x16x32_bf16 v[26:29], v[240:243], v[200:203], v[26:29]
	v_mfma_f32_16x16x32_bf16 v[22:25], v[232:235], v[208:211], v[22:25]
	v_mfma_f32_16x16x32_bf16 v[18:21], v[240:243], v[208:211], v[18:21]
	v_mfma_f32_16x16x32_bf16 v[14:17], v[232:235], v[216:219], v[14:17]
	v_mfma_f32_16x16x32_bf16 v[10:13], v[240:243], v[216:219], v[10:13]
	v_mfma_f32_16x16x32_bf16 v[6:9], v[232:235], v[224:227], v[6:9]
	v_mfma_f32_16x16x32_bf16 v[2:5], v[240:243], v[224:227], v[2:5]
	s_add_i32 s9, s9, 2
	s_add_u32 s36, s36, 0x100
	s_addc_u32 s37, s37, 0
	s_cmp_lt_u32 s9, 12
	s_barrier
	s_cbranch_scc1 .LBB0_2247
	v_readfirstlane_b32 s9, v175
	v_lshl_add_u64 v[140:141], v[140:141], 0, s[30:31]
	s_mov_b32 m0, s9
	v_readfirstlane_b32 s9, v176
	ds_read_b128 v[144:147], v162
	ds_read_b128 v[148:151], v162 offset:1024
	ds_read_b128 v[170:173], v162 offset:2048
	ds_read_b128 v[178:181], v162 offset:3072
	ds_read_b128 v[182:185], v163
	ds_read_b128 v[186:189], v163 offset:1024
	ds_read_b128 v[190:193], v164
	ds_read_b128 v[194:197], v164 offset:1024
	ds_read_b128 v[200:203], v165
	ds_read_b128 v[204:207], v165 offset:1024
	ds_read_b128 v[208:211], v166
	ds_read_b128 v[212:215], v166 offset:1024
	global_load_lds_dwordx4 v[140:141], off
	v_lshl_add_u64 v[140:141], v[142:143], 0, s[30:31]
	s_mov_b32 m0, s9
	s_nop 0
	global_load_lds_dwordx4 v[140:141], off
	s_barrier
	s_waitcnt lgkmcnt(0)
	v_mfma_f32_16x16x32_bf16 v[126:129], v[144:147], v[182:185], v[126:129]
	v_mfma_f32_16x16x32_bf16 v[122:125], v[170:173], v[182:185], v[122:125]
	v_mfma_f32_16x16x32_bf16 v[114:117], v[170:173], v[190:193], v[114:117]
	v_mfma_f32_16x16x32_bf16 v[106:109], v[170:173], v[200:203], v[106:109]
	v_mfma_f32_16x16x32_bf16 v[98:101], v[170:173], v[208:211], v[98:101]
	v_mfma_f32_16x16x32_bf16 v[126:129], v[148:151], v[186:189], v[126:129]
	v_mfma_f32_16x16x32_bf16 v[122:125], v[178:181], v[186:189], v[122:125]
	v_mfma_f32_16x16x32_bf16 v[118:121], v[144:147], v[190:193], v[118:121]
	v_mfma_f32_16x16x32_bf16 v[114:117], v[178:181], v[194:197], v[114:117]
	v_mfma_f32_16x16x32_bf16 v[110:113], v[144:147], v[200:203], v[110:113]
	v_mfma_f32_16x16x32_bf16 v[106:109], v[178:181], v[204:207], v[106:109]
	v_mfma_f32_16x16x32_bf16 v[102:105], v[144:147], v[208:211], v[102:105]
	v_mfma_f32_16x16x32_bf16 v[98:101], v[178:181], v[212:215], v[98:101]
	v_mfma_f32_16x16x32_bf16 v[140:143], v[148:151], v[194:197], v[118:121]
	v_mfma_f32_16x16x32_bf16 v[174:177], v[148:151], v[204:207], v[110:113]
	v_mfma_f32_16x16x32_bf16 v[216:219], v[148:151], v[212:215], v[102:105]
	s_barrier
	s_nop 1
	ds_read_b128 v[102:105], v167
	ds_read_b128 v[110:113], v167 offset:1024
	ds_read_b128 v[118:121], v167 offset:2048
	ds_read_b128 v[220:223], v167 offset:3072
	s_barrier
	s_waitcnt lgkmcnt(0)
	v_mfma_f32_16x16x32_bf16 v[90:93], v[118:121], v[182:185], v[90:93]
	v_mfma_f32_16x16x32_bf16 v[82:85], v[118:121], v[190:193], v[82:85]
	v_mfma_f32_16x16x32_bf16 v[74:77], v[118:121], v[200:203], v[74:77]
	v_mfma_f32_16x16x32_bf16 v[66:69], v[118:121], v[208:211], v[66:69]
	v_mfma_f32_16x16x32_bf16 v[94:97], v[102:105], v[182:185], v[94:97]
	v_mfma_f32_16x16x32_bf16 v[90:93], v[220:223], v[186:189], v[90:93]
	v_mfma_f32_16x16x32_bf16 v[86:89], v[102:105], v[190:193], v[86:89]
	v_mfma_f32_16x16x32_bf16 v[82:85], v[220:223], v[194:197], v[82:85]
	v_mfma_f32_16x16x32_bf16 v[78:81], v[102:105], v[200:203], v[78:81]
	v_mfma_f32_16x16x32_bf16 v[74:77], v[220:223], v[204:207], v[74:77]
	v_mfma_f32_16x16x32_bf16 v[70:73], v[102:105], v[208:211], v[70:73]
	v_mfma_f32_16x16x32_bf16 v[66:69], v[220:223], v[212:215], v[66:69]
	v_mfma_f32_16x16x32_bf16 v[224:227], v[110:113], v[186:189], v[94:97]
	v_mfma_f32_16x16x32_bf16 v[182:185], v[110:113], v[194:197], v[86:89]
	v_mfma_f32_16x16x32_bf16 v[186:189], v[110:113], v[204:207], v[78:81]
	v_mfma_f32_16x16x32_bf16 v[190:193], v[110:113], v[212:215], v[70:73]
	s_barrier
	s_nop 0
	ds_read_b128 v[70:73], v163 offset:16384
	ds_read_b128 v[78:81], v163 offset:17408
	ds_read_b128 v[86:89], v164 offset:16384
	ds_read_b128 v[94:97], v164 offset:17408
	ds_read_b128 v[194:197], v165 offset:16384
	ds_read_b128 v[200:203], v165 offset:17408
	ds_read_b128 v[204:207], v166 offset:16384
	ds_read_b128 v[208:211], v166 offset:17408
	s_waitcnt vmcnt(4)
	s_barrier
	s_waitcnt lgkmcnt(0)
	v_mfma_f32_16x16x32_bf16 v[62:65], v[144:147], v[70:73], v[62:65]
	v_mfma_f32_16x16x32_bf16 v[58:61], v[170:173], v[70:73], v[58:61]
	v_mfma_f32_16x16x32_bf16 v[54:57], v[144:147], v[86:89], v[54:57]
	v_mfma_f32_16x16x32_bf16 v[50:53], v[170:173], v[86:89], v[50:53]
	v_mfma_f32_16x16x32_bf16 v[38:41], v[144:147], v[204:207], v[38:41]
	v_mfma_f32_16x16x32_bf16 v[34:37], v[170:173], v[204:207], v[34:37]
	v_mfma_f32_16x16x32_bf16 v[62:65], v[148:151], v[78:81], v[62:65]
	v_mfma_f32_16x16x32_bf16 v[58:61], v[178:181], v[78:81], v[58:61]
	v_mfma_f32_16x16x32_bf16 v[54:57], v[148:151], v[94:97], v[54:57]
	v_mfma_f32_16x16x32_bf16 v[50:53], v[178:181], v[94:97], v[50:53]
	v_mfma_f32_16x16x32_bf16 v[46:49], v[144:147], v[194:197], v[46:49]
	v_mfma_f32_16x16x32_bf16 v[42:45], v[170:173], v[194:197], v[42:45]
	v_mfma_f32_16x16x32_bf16 v[38:41], v[148:151], v[208:211], v[38:41]
	v_mfma_f32_16x16x32_bf16 v[34:37], v[178:181], v[208:211], v[34:37]
	v_mfma_f32_16x16x32_bf16 v[212:215], v[148:151], v[200:203], v[46:49]
	v_mfma_f32_16x16x32_bf16 v[228:231], v[178:181], v[200:203], v[42:45]
	v_mfma_f32_16x16x32_bf16 v[22:25], v[102:105], v[86:89], v[22:25]
	v_mfma_f32_16x16x32_bf16 v[18:21], v[118:121], v[86:89], v[18:21]
	v_mfma_f32_16x16x32_bf16 v[6:9], v[102:105], v[204:207], v[6:9]
	v_mfma_f32_16x16x32_bf16 v[2:5], v[118:121], v[204:207], v[2:5]
	v_mfma_f32_16x16x32_bf16 v[30:33], v[102:105], v[70:73], v[30:33]
	v_mfma_f32_16x16x32_bf16 v[26:29], v[118:121], v[70:73], v[26:29]
	v_mfma_f32_16x16x32_bf16 v[22:25], v[110:113], v[94:97], v[22:25]
	v_mfma_f32_16x16x32_bf16 v[18:21], v[220:223], v[94:97], v[18:21]
	v_mfma_f32_16x16x32_bf16 v[14:17], v[102:105], v[194:197], v[14:17]
	v_mfma_f32_16x16x32_bf16 v[10:13], v[118:121], v[194:197], v[10:13]
	v_mfma_f32_16x16x32_bf16 v[6:9], v[110:113], v[208:211], v[6:9]
	v_mfma_f32_16x16x32_bf16 v[2:5], v[220:223], v[208:211], v[2:5]
	v_mfma_f32_16x16x32_bf16 v[144:147], v[110:113], v[78:81], v[30:33]
	v_mfma_f32_16x16x32_bf16 v[148:151], v[220:223], v[78:81], v[26:29]
	v_mfma_f32_16x16x32_bf16 v[170:173], v[110:113], v[200:203], v[14:17]
	v_mfma_f32_16x16x32_bf16 v[178:181], v[220:223], v[200:203], v[10:13]
	s_barrier
	s_nop 0
	ds_read_b128 v[10:13], v168
	ds_read_b128 v[14:17], v168 offset:1024
	ds_read_b128 v[194:197], v168 offset:2048
	ds_read_b128 v[200:203], v168 offset:3072
	ds_read_b128 v[26:29], v163 offset:32768
	ds_read_b128 v[30:33], v163 offset:33792
	ds_read_b128 v[42:45], v164 offset:32768
	ds_read_b128 v[46:49], v164 offset:33792
	ds_read_b128 v[204:207], v165 offset:32768
	ds_read_b128 v[208:211], v165 offset:33792
	ds_read_b128 v[220:223], v166 offset:32768
	ds_read_b128 v[232:235], v166 offset:33792
	s_waitcnt vmcnt(2)
	s_barrier
	s_waitcnt lgkmcnt(0)
	v_mfma_f32_16x16x32_bf16 v[70:73], v[10:13], v[26:29], v[126:129]
	v_mfma_f32_16x16x32_bf16 v[126:129], v[14:17], v[30:33], v[70:73]
	v_mfma_f32_16x16x32_bf16 v[70:73], v[194:197], v[26:29], v[122:125]
	v_mfma_f32_16x16x32_bf16 v[118:121], v[200:203], v[30:33], v[70:73]
	v_mfma_f32_16x16x32_bf16 v[70:73], v[10:13], v[42:45], v[140:143]
	v_mfma_f32_16x16x32_bf16 v[110:113], v[14:17], v[46:49], v[70:73]
	v_mfma_f32_16x16x32_bf16 v[70:73], v[194:197], v[42:45], v[114:117]
	v_mfma_f32_16x16x32_bf16 v[102:105], v[200:203], v[46:49], v[70:73]
	v_mfma_f32_16x16x32_bf16 v[70:73], v[10:13], v[204:207], v[174:177]
	v_mfma_f32_16x16x32_bf16 v[94:97], v[14:17], v[208:211], v[70:73]
	v_mfma_f32_16x16x32_bf16 v[70:73], v[194:197], v[204:207], v[106:109]
	v_mfma_f32_16x16x32_bf16 v[86:89], v[200:203], v[208:211], v[70:73]
	v_mfma_f32_16x16x32_bf16 v[70:73], v[10:13], v[220:223], v[216:219]
	v_mfma_f32_16x16x32_bf16 v[78:81], v[14:17], v[232:235], v[70:73]
	v_mfma_f32_16x16x32_bf16 v[70:73], v[194:197], v[220:223], v[98:101]
	v_mfma_f32_16x16x32_bf16 v[70:73], v[200:203], v[232:235], v[70:73]
	s_barrier
	ds_read_b128 v[140:143], v169
	ds_read_b128 v[174:177], v169 offset:1024
	ds_read_b128 v[216:219], v169 offset:2048
	ds_read_b128 v[236:239], v169 offset:3072
	s_waitcnt vmcnt(0)
	s_barrier
	s_waitcnt lgkmcnt(0)
	v_mfma_f32_16x16x32_bf16 v[98:101], v[140:143], v[26:29], v[224:227]
	v_mfma_f32_16x16x32_bf16 v[26:29], v[216:219], v[26:29], v[90:93]
	v_mfma_f32_16x16x32_bf16 v[114:117], v[236:239], v[30:33], v[26:29]
	v_mfma_f32_16x16x32_bf16 v[26:29], v[140:143], v[42:45], v[182:185]
	v_mfma_f32_16x16x32_bf16 v[106:109], v[174:177], v[46:49], v[26:29]
	v_mfma_f32_16x16x32_bf16 v[26:29], v[216:219], v[42:45], v[82:85]
	v_mfma_f32_16x16x32_bf16 v[122:125], v[174:177], v[30:33], v[98:101]
	v_mfma_f32_16x16x32_bf16 v[98:101], v[236:239], v[46:49], v[26:29]
	v_mfma_f32_16x16x32_bf16 v[26:29], v[140:143], v[204:207], v[186:189]
	v_mfma_f32_16x16x32_bf16 v[90:93], v[174:177], v[208:211], v[26:29]
	v_mfma_f32_16x16x32_bf16 v[26:29], v[216:219], v[204:207], v[74:77]
	v_mfma_f32_16x16x32_bf16 v[82:85], v[236:239], v[208:211], v[26:29]
	v_mfma_f32_16x16x32_bf16 v[26:29], v[140:143], v[220:223], v[190:193]
	v_mfma_f32_16x16x32_bf16 v[74:77], v[174:177], v[232:235], v[26:29]
	v_mfma_f32_16x16x32_bf16 v[26:29], v[216:219], v[220:223], v[66:69]
	v_mfma_f32_16x16x32_bf16 v[66:69], v[236:239], v[232:235], v[26:29]
	s_barrier
	ds_read_b128 v[182:185], v163 offset:49152
	ds_read_b128 v[186:189], v163 offset:50176
	ds_read_b128 v[190:193], v164 offset:49152
	ds_read_b128 v[204:207], v164 offset:50176
	ds_read_b128 v[208:211], v165 offset:49152
	ds_read_b128 v[220:223], v165 offset:50176
	ds_read_b128 v[224:227], v166 offset:49152
	ds_read_b128 v[232:235], v166 offset:50176
	s_barrier
	s_waitcnt lgkmcnt(0)
	v_mfma_f32_16x16x32_bf16 v[26:29], v[10:13], v[182:185], v[62:65]
	v_mfma_f32_16x16x32_bf16 v[62:65], v[14:17], v[186:189], v[26:29]
	v_mfma_f32_16x16x32_bf16 v[26:29], v[194:197], v[182:185], v[58:61]
	v_mfma_f32_16x16x32_bf16 v[58:61], v[200:203], v[186:189], v[26:29]
	v_mfma_f32_16x16x32_bf16 v[26:29], v[10:13], v[190:193], v[54:57]
	v_mfma_f32_16x16x32_bf16 v[46:49], v[14:17], v[204:207], v[26:29]
	v_mfma_f32_16x16x32_bf16 v[26:29], v[194:197], v[190:193], v[50:53]
	v_mfma_f32_16x16x32_bf16 v[42:45], v[200:203], v[204:207], v[26:29]
	v_mfma_f32_16x16x32_bf16 v[26:29], v[10:13], v[208:211], v[212:215]
	v_mfma_f32_16x16x32_bf16 v[10:13], v[10:13], v[224:227], v[38:41]
	v_mfma_f32_16x16x32_bf16 v[30:33], v[14:17], v[220:223], v[26:29]
	v_mfma_f32_16x16x32_bf16 v[26:29], v[194:197], v[208:211], v[228:231]
	v_mfma_f32_16x16x32_bf16 v[14:17], v[14:17], v[232:235], v[10:13]
	v_mfma_f32_16x16x32_bf16 v[10:13], v[194:197], v[224:227], v[34:37]
	v_mfma_f32_16x16x32_bf16 v[26:29], v[200:203], v[220:223], v[26:29]
	v_mfma_f32_16x16x32_bf16 v[10:13], v[200:203], v[232:235], v[10:13]
	v_mfma_f32_16x16x32_bf16 v[34:37], v[140:143], v[182:185], v[144:147]
	v_mfma_f32_16x16x32_bf16 v[54:57], v[174:177], v[186:189], v[34:37]
	v_mfma_f32_16x16x32_bf16 v[34:37], v[216:219], v[182:185], v[148:151]
	v_mfma_f32_16x16x32_bf16 v[18:21], v[216:219], v[190:193], v[18:21]
	v_mfma_f32_16x16x32_bf16 v[50:53], v[236:239], v[186:189], v[34:37]
	v_mfma_f32_16x16x32_bf16 v[22:25], v[140:143], v[190:193], v[22:25]
	v_mfma_f32_16x16x32_bf16 v[34:37], v[236:239], v[204:207], v[18:21]
	v_mfma_f32_16x16x32_bf16 v[18:21], v[140:143], v[208:211], v[170:173]
	v_mfma_f32_16x16x32_bf16 v[38:41], v[174:177], v[204:207], v[22:25]
	v_mfma_f32_16x16x32_bf16 v[22:25], v[174:177], v[220:223], v[18:21]
	v_mfma_f32_16x16x32_bf16 v[18:21], v[216:219], v[208:211], v[178:181]
	v_mfma_f32_16x16x32_bf16 v[6:9], v[140:143], v[224:227], v[6:9]
	v_mfma_f32_16x16x32_bf16 v[2:5], v[216:219], v[224:227], v[2:5]
	v_mfma_f32_16x16x32_bf16 v[18:21], v[236:239], v[220:223], v[18:21]
	v_mfma_f32_16x16x32_bf16 v[6:9], v[174:177], v[232:235], v[6:9]
	v_mfma_f32_16x16x32_bf16 v[2:5], v[236:239], v[232:235], v[2:5]
	s_barrier
	s_and_saveexec_b64 s[36:37], s[6:7]
	v_readlane_b32 s64, v254, 29
	v_readlane_b32 s65, v254, 30
	v_readlane_b32 s66, v254, 31
	v_readlane_b32 s67, v254, 32
	v_readlane_b32 s68, v254, 33
	v_readlane_b32 s69, v254, 34
	v_readlane_b32 s70, v254, 35
	v_readlane_b32 s71, v254, 36
	v_readlane_b32 s72, v254, 37
	v_readlane_b32 s73, v254, 38
	v_readlane_b32 s74, v254, 39
	v_readlane_b32 s75, v254, 40
	v_readlane_b32 s76, v254, 41
	v_readlane_b32 s77, v254, 42
	v_readlane_b32 s78, v254, 43
	v_readlane_b32 s79, v254, 44
	s_cbranch_execz .LBB0_2250
	s_barrier

.LBB0_2359:
	ds_read_b128 v[150:153], v192
	ds_read_b128 v[154:157], v192 offset:1024
	ds_read_b128 v[158:161], v192 offset:2048
	ds_read_b128 v[172:175], v192 offset:3072
	v_add_u32_e32 v148, 0xc000, v183
	v_lshl_add_u64 v[180:181], s[62:63], 0, v[138:139]
	v_readfirstlane_b32 s61, v148
	v_add_u32_e32 v149, 0xe000, v183
	v_lshl_add_u64 v[230:231], v[180:181], 0, s[18:19]
	s_mov_b32 m0, s61
	v_lshl_add_u64 v[246:247], s[62:63], 0, v[140:141]
	v_readfirstlane_b32 s61, v149
	ds_read_b128 v[176:179], v193
	ds_read_b128 v[202:205], v193 offset:1024
	ds_read_b128 v[206:209], v194
	ds_read_b128 v[210:213], v194 offset:1024
	ds_read_b128 v[214:217], v195
	ds_read_b128 v[218:221], v195 offset:1024
	ds_read_b128 v[222:225], v196
	ds_read_b128 v[226:229], v196 offset:1024
	global_load_lds_dwordx4 v[230:231], off
	v_lshl_add_u64 v[230:231], v[246:247], 0, s[18:19]
	s_mov_b32 m0, s61
	s_nop 0
	global_load_lds_dwordx4 v[230:231], off
	s_waitcnt lgkmcnt(8)
	s_barrier
	s_waitcnt lgkmcnt(0)
	v_mfma_f32_16x16x32_bf16 v[126:129], v[150:153], v[176:179], v[126:129]
	v_mfma_f32_16x16x32_bf16 v[122:125], v[158:161], v[176:179], v[122:125]
	v_mfma_f32_16x16x32_bf16 v[118:121], v[150:153], v[206:209], v[118:121]
	v_mfma_f32_16x16x32_bf16 v[114:117], v[158:161], v[206:209], v[114:117]
	v_mfma_f32_16x16x32_bf16 v[110:113], v[150:153], v[214:217], v[110:113]
	v_mfma_f32_16x16x32_bf16 v[106:109], v[158:161], v[214:217], v[106:109]
	v_mfma_f32_16x16x32_bf16 v[102:105], v[150:153], v[222:225], v[102:105]
	v_mfma_f32_16x16x32_bf16 v[98:101], v[158:161], v[222:225], v[98:101]
	v_mfma_f32_16x16x32_bf16 v[126:129], v[154:157], v[202:205], v[126:129]
	v_mfma_f32_16x16x32_bf16 v[122:125], v[172:175], v[202:205], v[122:125]
	v_mfma_f32_16x16x32_bf16 v[118:121], v[154:157], v[210:213], v[118:121]
	v_mfma_f32_16x16x32_bf16 v[114:117], v[172:175], v[210:213], v[114:117]
	v_mfma_f32_16x16x32_bf16 v[110:113], v[154:157], v[218:221], v[110:113]
	v_mfma_f32_16x16x32_bf16 v[106:109], v[172:175], v[218:221], v[106:109]
	v_mfma_f32_16x16x32_bf16 v[102:105], v[154:157], v[226:229], v[102:105]
	v_mfma_f32_16x16x32_bf16 v[98:101], v[172:175], v[226:229], v[98:101]
	s_barrier
	v_lshl_add_u64 v[248:249], s[62:63], 0, v[134:135]
	v_readfirstlane_b32 s61, v188
	v_lshl_add_u64 v[250:251], v[248:249], 0, s[20:21]
	s_mov_b32 m0, s61
	ds_read_b128 v[230:233], v197
	ds_read_b128 v[234:237], v197 offset:1024
	ds_read_b128 v[238:241], v197 offset:2048
	ds_read_b128 v[242:245], v197 offset:3072
	global_load_lds_dwordx4 v[250:251], off
	v_lshl_add_u64 v[250:251], s[62:63], 0, v[136:137]
	v_readfirstlane_b32 s61, v189
	v_lshl_add_u64 v[252:253], v[250:251], 0, s[20:21]
	s_mov_b32 m0, s61
	s_nop 0
	global_load_lds_dwordx4 v[252:253], off
	s_barrier
	s_waitcnt lgkmcnt(0)
	v_mfma_f32_16x16x32_bf16 v[94:97], v[230:233], v[176:179], v[94:97]
	v_mfma_f32_16x16x32_bf16 v[90:93], v[238:241], v[176:179], v[90:93]
	v_mfma_f32_16x16x32_bf16 v[86:89], v[230:233], v[206:209], v[86:89]
	v_mfma_f32_16x16x32_bf16 v[82:85], v[238:241], v[206:209], v[82:85]
	v_mfma_f32_16x16x32_bf16 v[78:81], v[230:233], v[214:217], v[78:81]
	v_mfma_f32_16x16x32_bf16 v[74:77], v[238:241], v[214:217], v[74:77]
	v_mfma_f32_16x16x32_bf16 v[70:73], v[230:233], v[222:225], v[70:73]
	v_mfma_f32_16x16x32_bf16 v[66:69], v[238:241], v[222:225], v[66:69]
	v_mfma_f32_16x16x32_bf16 v[94:97], v[234:237], v[202:205], v[94:97]
	v_mfma_f32_16x16x32_bf16 v[90:93], v[242:245], v[202:205], v[90:93]
	v_mfma_f32_16x16x32_bf16 v[86:89], v[234:237], v[210:213], v[86:89]
	v_mfma_f32_16x16x32_bf16 v[82:85], v[242:245], v[210:213], v[82:85]
	v_mfma_f32_16x16x32_bf16 v[78:81], v[234:237], v[218:221], v[78:81]
	v_mfma_f32_16x16x32_bf16 v[74:77], v[242:245], v[218:221], v[74:77]
	v_mfma_f32_16x16x32_bf16 v[70:73], v[234:237], v[226:229], v[70:73]
	v_mfma_f32_16x16x32_bf16 v[66:69], v[242:245], v[226:229], v[66:69]
	v_readfirstlane_b32 s61, v183
	v_lshl_add_u64 v[252:253], v[180:181], 0, s[22:23]
	s_mov_b32 m0, s61
	v_readfirstlane_b32 s61, v184
	s_barrier
	ds_read_b128 v[176:179], v193 offset:16384
	ds_read_b128 v[202:205], v193 offset:17408
	ds_read_b128 v[206:209], v194 offset:16384
	ds_read_b128 v[210:213], v194 offset:17408
	ds_read_b128 v[214:217], v195 offset:16384
	ds_read_b128 v[218:221], v195 offset:17408
	ds_read_b128 v[222:225], v196 offset:16384
	ds_read_b128 v[226:229], v196 offset:17408
	global_load_lds_dwordx4 v[252:253], off
	v_lshl_add_u64 v[252:253], v[246:247], 0, s[22:23]
	s_mov_b32 m0, s61
	s_nop 0
	global_load_lds_dwordx4 v[252:253], off
	s_barrier
	s_waitcnt lgkmcnt(0)
	v_mfma_f32_16x16x32_bf16 v[62:65], v[150:153], v[176:179], v[62:65]
	v_mfma_f32_16x16x32_bf16 v[58:61], v[158:161], v[176:179], v[58:61]
	v_mfma_f32_16x16x32_bf16 v[54:57], v[150:153], v[206:209], v[54:57]
	v_mfma_f32_16x16x32_bf16 v[50:53], v[158:161], v[206:209], v[50:53]
	v_mfma_f32_16x16x32_bf16 v[46:49], v[150:153], v[214:217], v[46:49]
	v_mfma_f32_16x16x32_bf16 v[42:45], v[158:161], v[214:217], v[42:45]
	v_mfma_f32_16x16x32_bf16 v[38:41], v[150:153], v[222:225], v[38:41]
	v_mfma_f32_16x16x32_bf16 v[34:37], v[158:161], v[222:225], v[34:37]
	v_mfma_f32_16x16x32_bf16 v[62:65], v[154:157], v[202:205], v[62:65]
	v_mfma_f32_16x16x32_bf16 v[58:61], v[172:175], v[202:205], v[58:61]
	v_mfma_f32_16x16x32_bf16 v[54:57], v[154:157], v[210:213], v[54:57]
	v_mfma_f32_16x16x32_bf16 v[50:53], v[172:175], v[210:213], v[50:53]
	v_mfma_f32_16x16x32_bf16 v[46:49], v[154:157], v[218:221], v[46:49]
	v_mfma_f32_16x16x32_bf16 v[42:45], v[172:175], v[218:221], v[42:45]
	v_mfma_f32_16x16x32_bf16 v[38:41], v[154:157], v[226:229], v[38:41]
	v_mfma_f32_16x16x32_bf16 v[34:37], v[172:175], v[226:229], v[34:37]
	s_barrier
	v_readfirstlane_b32 s61, v190
	v_lshl_add_u64 v[150:151], v[248:249], 0, s[24:25]
	s_mov_b32 m0, s61
	v_readfirstlane_b32 s61, v191
	global_load_lds_dwordx4 v[150:151], off
	v_lshl_add_u64 v[150:151], v[250:251], 0, s[24:25]
	s_mov_b32 m0, s61
	s_nop 0
	global_load_lds_dwordx4 v[150:151], off
	s_waitcnt vmcnt(6)
	s_barrier
	v_mfma_f32_16x16x32_bf16 v[30:33], v[230:233], v[176:179], v[30:33]
	v_mfma_f32_16x16x32_bf16 v[26:29], v[238:241], v[176:179], v[26:29]
	v_mfma_f32_16x16x32_bf16 v[22:25], v[230:233], v[206:209], v[22:25]
	v_mfma_f32_16x16x32_bf16 v[18:21], v[238:241], v[206:209], v[18:21]
	v_mfma_f32_16x16x32_bf16 v[14:17], v[230:233], v[214:217], v[14:17]
	v_mfma_f32_16x16x32_bf16 v[10:13], v[238:241], v[214:217], v[10:13]
	v_mfma_f32_16x16x32_bf16 v[6:9], v[230:233], v[222:225], v[6:9]
	v_mfma_f32_16x16x32_bf16 v[2:5], v[238:241], v[222:225], v[2:5]
	v_mfma_f32_16x16x32_bf16 v[30:33], v[234:237], v[202:205], v[30:33]
	v_mfma_f32_16x16x32_bf16 v[26:29], v[242:245], v[202:205], v[26:29]
	v_mfma_f32_16x16x32_bf16 v[22:25], v[234:237], v[210:213], v[22:25]
	v_mfma_f32_16x16x32_bf16 v[18:21], v[242:245], v[210:213], v[18:21]
	v_mfma_f32_16x16x32_bf16 v[14:17], v[234:237], v[218:221], v[14:17]
	v_mfma_f32_16x16x32_bf16 v[10:13], v[242:245], v[218:221], v[10:13]
	v_mfma_f32_16x16x32_bf16 v[6:9], v[234:237], v[226:229], v[6:9]
	v_mfma_f32_16x16x32_bf16 v[2:5], v[242:245], v[226:229], v[2:5]
	s_barrier
	ds_read_b128 v[150:153], v199
	ds_read_b128 v[154:157], v199 offset:1024
	ds_read_b128 v[158:161], v199 offset:2048
	ds_read_b128 v[172:175], v199 offset:3072
	v_readfirstlane_b32 s61, v185
	v_lshl_add_u64 v[230:231], v[180:181], 0, s[26:27]
	s_mov_b32 m0, s61
	v_readfirstlane_b32 s61, v186
	ds_read_b128 v[176:179], v193 offset:32768
	ds_read_b128 v[202:205], v193 offset:33792
	ds_read_b128 v[206:209], v194 offset:32768
	ds_read_b128 v[210:213], v194 offset:33792
	ds_read_b128 v[214:217], v195 offset:32768
	ds_read_b128 v[218:221], v195 offset:33792
	ds_read_b128 v[222:225], v196 offset:32768
	ds_read_b128 v[226:229], v196 offset:33792
	global_load_lds_dwordx4 v[230:231], off
	v_lshl_add_u64 v[230:231], v[246:247], 0, s[26:27]
	s_mov_b32 m0, s61
	s_nop 0
	global_load_lds_dwordx4 v[230:231], off
	s_waitcnt lgkmcnt(8)
	s_barrier
	s_waitcnt lgkmcnt(0)
	v_mfma_f32_16x16x32_bf16 v[126:129], v[150:153], v[176:179], v[126:129]
	v_mfma_f32_16x16x32_bf16 v[122:125], v[158:161], v[176:179], v[122:125]
	v_mfma_f32_16x16x32_bf16 v[118:121], v[150:153], v[206:209], v[118:121]
	v_mfma_f32_16x16x32_bf16 v[114:117], v[158:161], v[206:209], v[114:117]
	v_mfma_f32_16x16x32_bf16 v[110:113], v[150:153], v[214:217], v[110:113]
	v_mfma_f32_16x16x32_bf16 v[106:109], v[158:161], v[214:217], v[106:109]
	v_mfma_f32_16x16x32_bf16 v[102:105], v[150:153], v[222:225], v[102:105]
	v_mfma_f32_16x16x32_bf16 v[98:101], v[158:161], v[222:225], v[98:101]
	v_mfma_f32_16x16x32_bf16 v[126:129], v[154:157], v[202:205], v[126:129]
	v_mfma_f32_16x16x32_bf16 v[122:125], v[172:175], v[202:205], v[122:125]
	v_mfma_f32_16x16x32_bf16 v[118:121], v[154:157], v[210:213], v[118:121]
	v_mfma_f32_16x16x32_bf16 v[114:117], v[172:175], v[210:213], v[114:117]
	v_mfma_f32_16x16x32_bf16 v[110:113], v[154:157], v[218:221], v[110:113]
	v_mfma_f32_16x16x32_bf16 v[106:109], v[172:175], v[218:221], v[106:109]
	v_mfma_f32_16x16x32_bf16 v[102:105], v[154:157], v[226:229], v[102:105]
	v_mfma_f32_16x16x32_bf16 v[98:101], v[172:175], v[226:229], v[98:101]
	s_barrier
	v_readfirstlane_b32 s61, v142
	v_lshl_add_u64 v[252:253], v[248:249], 0, s[28:29]
	s_mov_b32 m0, s61
	v_readfirstlane_b32 s61, v143
	ds_read_b128 v[230:233], v200
	ds_read_b128 v[234:237], v200 offset:1024
	ds_read_b128 v[238:241], v200 offset:2048
	ds_read_b128 v[242:245], v200 offset:3072
	global_load_lds_dwordx4 v[252:253], off
	v_lshl_add_u64 v[252:253], v[250:251], 0, s[28:29]
	s_mov_b32 m0, s61
	s_nop 0
	global_load_lds_dwordx4 v[252:253], off
	s_barrier
	s_waitcnt lgkmcnt(0)
	v_mfma_f32_16x16x32_bf16 v[94:97], v[230:233], v[176:179], v[94:97]
	v_mfma_f32_16x16x32_bf16 v[90:93], v[238:241], v[176:179], v[90:93]
	v_mfma_f32_16x16x32_bf16 v[86:89], v[230:233], v[206:209], v[86:89]
	v_mfma_f32_16x16x32_bf16 v[82:85], v[238:241], v[206:209], v[82:85]
	v_mfma_f32_16x16x32_bf16 v[78:81], v[230:233], v[214:217], v[78:81]
	v_mfma_f32_16x16x32_bf16 v[74:77], v[238:241], v[214:217], v[74:77]
	v_mfma_f32_16x16x32_bf16 v[70:73], v[230:233], v[222:225], v[70:73]
	v_mfma_f32_16x16x32_bf16 v[66:69], v[238:241], v[222:225], v[66:69]
	v_mfma_f32_16x16x32_bf16 v[94:97], v[234:237], v[202:205], v[94:97]
	v_mfma_f32_16x16x32_bf16 v[90:93], v[242:245], v[202:205], v[90:93]
	v_mfma_f32_16x16x32_bf16 v[86:89], v[234:237], v[210:213], v[86:89]
	v_mfma_f32_16x16x32_bf16 v[82:85], v[242:245], v[210:213], v[82:85]
	v_mfma_f32_16x16x32_bf16 v[78:81], v[234:237], v[218:221], v[78:81]
	v_mfma_f32_16x16x32_bf16 v[74:77], v[242:245], v[218:221], v[74:77]
	v_mfma_f32_16x16x32_bf16 v[70:73], v[234:237], v[226:229], v[70:73]
	v_mfma_f32_16x16x32_bf16 v[66:69], v[242:245], v[226:229], v[66:69]
	v_readfirstlane_b32 s61, v144
	v_lshl_add_u64 v[180:181], v[180:181], 0, s[30:31]
	s_mov_b32 m0, s61
	v_readfirstlane_b32 s61, v145
	s_barrier
	ds_read_b128 v[176:179], v193 offset:49152
	ds_read_b128 v[202:205], v193 offset:50176
	ds_read_b128 v[206:209], v194 offset:49152
	ds_read_b128 v[210:213], v194 offset:50176
	ds_read_b128 v[214:217], v195 offset:49152
	ds_read_b128 v[218:221], v195 offset:50176
	ds_read_b128 v[222:225], v196 offset:49152
	ds_read_b128 v[226:229], v196 offset:50176
	global_load_lds_dwordx4 v[180:181], off
	v_lshl_add_u64 v[180:181], v[246:247], 0, s[30:31]
	s_mov_b32 m0, s61
	s_nop 0
	global_load_lds_dwordx4 v[180:181], off
	s_barrier
	s_waitcnt lgkmcnt(0)
	v_mfma_f32_16x16x32_bf16 v[62:65], v[150:153], v[176:179], v[62:65]
	v_mfma_f32_16x16x32_bf16 v[58:61], v[158:161], v[176:179], v[58:61]
	v_mfma_f32_16x16x32_bf16 v[54:57], v[150:153], v[206:209], v[54:57]
	v_mfma_f32_16x16x32_bf16 v[50:53], v[158:161], v[206:209], v[50:53]
	v_mfma_f32_16x16x32_bf16 v[46:49], v[150:153], v[214:217], v[46:49]
	v_mfma_f32_16x16x32_bf16 v[42:45], v[158:161], v[214:217], v[42:45]
	v_mfma_f32_16x16x32_bf16 v[38:41], v[150:153], v[222:225], v[38:41]
	v_mfma_f32_16x16x32_bf16 v[34:37], v[158:161], v[222:225], v[34:37]
	v_mfma_f32_16x16x32_bf16 v[62:65], v[154:157], v[202:205], v[62:65]
	v_mfma_f32_16x16x32_bf16 v[58:61], v[172:175], v[202:205], v[58:61]
	v_mfma_f32_16x16x32_bf16 v[54:57], v[154:157], v[210:213], v[54:57]
	v_mfma_f32_16x16x32_bf16 v[50:53], v[172:175], v[210:213], v[50:53]
	v_mfma_f32_16x16x32_bf16 v[46:49], v[154:157], v[218:221], v[46:49]
	v_mfma_f32_16x16x32_bf16 v[42:45], v[172:175], v[218:221], v[42:45]
	v_mfma_f32_16x16x32_bf16 v[38:41], v[154:157], v[226:229], v[38:41]
	v_mfma_f32_16x16x32_bf16 v[34:37], v[172:175], v[226:229], v[34:37]
	s_barrier
	v_readfirstlane_b32 s61, v146
	v_lshl_add_u64 v[150:151], v[248:249], 0, s[34:35]
	s_mov_b32 m0, s61
	v_readfirstlane_b32 s61, v147
	global_load_lds_dwordx4 v[150:151], off
	v_lshl_add_u64 v[150:151], v[250:251], 0, s[34:35]
	s_mov_b32 m0, s61
	s_nop 0
	global_load_lds_dwordx4 v[150:151], off
	s_waitcnt vmcnt(6)
	s_barrier
	v_mfma_f32_16x16x32_bf16 v[30:33], v[230:233], v[176:179], v[30:33]
	v_mfma_f32_16x16x32_bf16 v[26:29], v[238:241], v[176:179], v[26:29]
	v_mfma_f32_16x16x32_bf16 v[22:25], v[230:233], v[206:209], v[22:25]
	v_mfma_f32_16x16x32_bf16 v[18:21], v[238:241], v[206:209], v[18:21]
	v_mfma_f32_16x16x32_bf16 v[14:17], v[230:233], v[214:217], v[14:17]
	v_mfma_f32_16x16x32_bf16 v[10:13], v[238:241], v[214:217], v[10:13]
	v_mfma_f32_16x16x32_bf16 v[6:9], v[230:233], v[222:225], v[6:9]
	v_mfma_f32_16x16x32_bf16 v[2:5], v[238:241], v[222:225], v[2:5]
	v_mfma_f32_16x16x32_bf16 v[30:33], v[234:237], v[202:205], v[30:33]
	v_mfma_f32_16x16x32_bf16 v[26:29], v[242:245], v[202:205], v[26:29]
	v_mfma_f32_16x16x32_bf16 v[22:25], v[234:237], v[210:213], v[22:25]
	v_mfma_f32_16x16x32_bf16 v[18:21], v[242:245], v[210:213], v[18:21]
	v_mfma_f32_16x16x32_bf16 v[14:17], v[234:237], v[218:221], v[14:17]
	v_mfma_f32_16x16x32_bf16 v[10:13], v[242:245], v[218:221], v[10:13]
	v_mfma_f32_16x16x32_bf16 v[6:9], v[234:237], v[226:229], v[6:9]
	v_mfma_f32_16x16x32_bf16 v[2:5], v[242:245], v[226:229], v[2:5]
	s_add_i32 s39, s39, 2
	s_add_u32 s62, s62, 0x100
	s_addc_u32 s63, s63, 0
	s_cmp_lt_u32 s39, 12
	s_barrier
	s_cbranch_scc1 .LBB0_2359
	v_readfirstlane_b32 s39, v148
	v_lshl_add_u64 v[130:131], v[130:131], 0, s[36:37]
	s_mov_b32 m0, s39
	v_readfirstlane_b32 s39, v149
	ds_read_b128 v[134:137], v192
	ds_read_b128 v[138:141], v192 offset:1024
	ds_read_b128 v[142:145], v192 offset:2048
	ds_read_b128 v[150:153], v192 offset:3072
	ds_read_b128 v[154:157], v193
	ds_read_b128 v[158:161], v193 offset:1024
	ds_read_b128 v[172:175], v194
	ds_read_b128 v[176:179], v194 offset:1024
	ds_read_b128 v[202:205], v195
	ds_read_b128 v[206:209], v195 offset:1024
	ds_read_b128 v[210:213], v196
	ds_read_b128 v[214:217], v196 offset:1024
	global_load_lds_dwordx4 v[130:131], off
	v_lshl_add_u64 v[130:131], v[132:133], 0, s[36:37]
	s_mov_b32 m0, s39
	s_nop 0
	global_load_lds_dwordx4 v[130:131], off
	s_barrier
	s_waitcnt lgkmcnt(0)
	v_mfma_f32_16x16x32_bf16 v[126:129], v[134:137], v[154:157], v[126:129]
	v_mfma_f32_16x16x32_bf16 v[122:125], v[142:145], v[154:157], v[122:125]
	v_mfma_f32_16x16x32_bf16 v[118:121], v[134:137], v[172:175], v[118:121]
	v_mfma_f32_16x16x32_bf16 v[114:117], v[142:145], v[172:175], v[114:117]
	v_mfma_f32_16x16x32_bf16 v[110:113], v[134:137], v[202:205], v[110:113]
	v_mfma_f32_16x16x32_bf16 v[106:109], v[142:145], v[202:205], v[106:109]
	v_mfma_f32_16x16x32_bf16 v[102:105], v[134:137], v[210:213], v[102:105]
	v_mfma_f32_16x16x32_bf16 v[98:101], v[142:145], v[210:213], v[98:101]
	v_mfma_f32_16x16x32_bf16 v[126:129], v[138:141], v[158:161], v[126:129]
	v_mfma_f32_16x16x32_bf16 v[122:125], v[150:153], v[158:161], v[122:125]
	v_mfma_f32_16x16x32_bf16 v[118:121], v[138:141], v[176:179], v[118:121]
	v_mfma_f32_16x16x32_bf16 v[114:117], v[150:153], v[176:179], v[114:117]
	v_mfma_f32_16x16x32_bf16 v[110:113], v[138:141], v[206:209], v[110:113]
	v_mfma_f32_16x16x32_bf16 v[106:109], v[150:153], v[206:209], v[106:109]
	v_mfma_f32_16x16x32_bf16 v[102:105], v[138:141], v[214:217], v[102:105]
	v_mfma_f32_16x16x32_bf16 v[98:101], v[150:153], v[214:217], v[98:101]
	s_barrier
	ds_read_b128 v[130:133], v197
	ds_read_b128 v[146:149], v197 offset:1024
	ds_read_b128 v[218:221], v197 offset:2048
	ds_read_b128 v[222:225], v197 offset:3072
	s_barrier
	s_waitcnt lgkmcnt(0)
	v_mfma_f32_16x16x32_bf16 v[94:97], v[130:133], v[154:157], v[94:97]
	v_mfma_f32_16x16x32_bf16 v[90:93], v[218:221], v[154:157], v[90:93]
	v_mfma_f32_16x16x32_bf16 v[86:89], v[130:133], v[172:175], v[86:89]
	v_mfma_f32_16x16x32_bf16 v[82:85], v[218:221], v[172:175], v[82:85]
	v_mfma_f32_16x16x32_bf16 v[78:81], v[130:133], v[202:205], v[78:81]
	v_mfma_f32_16x16x32_bf16 v[74:77], v[218:221], v[202:205], v[74:77]
	v_mfma_f32_16x16x32_bf16 v[70:73], v[130:133], v[210:213], v[70:73]
	v_mfma_f32_16x16x32_bf16 v[66:69], v[218:221], v[210:213], v[66:69]
	v_mfma_f32_16x16x32_bf16 v[94:97], v[146:149], v[158:161], v[94:97]
	v_mfma_f32_16x16x32_bf16 v[90:93], v[222:225], v[158:161], v[90:93]
	v_mfma_f32_16x16x32_bf16 v[86:89], v[146:149], v[176:179], v[86:89]
	v_mfma_f32_16x16x32_bf16 v[82:85], v[222:225], v[176:179], v[82:85]
	v_mfma_f32_16x16x32_bf16 v[78:81], v[146:149], v[206:209], v[78:81]
	v_mfma_f32_16x16x32_bf16 v[74:77], v[222:225], v[206:209], v[74:77]
	v_mfma_f32_16x16x32_bf16 v[70:73], v[146:149], v[214:217], v[70:73]
	v_mfma_f32_16x16x32_bf16 v[66:69], v[222:225], v[214:217], v[66:69]
	s_barrier
	ds_read_b128 v[154:157], v193 offset:16384
	ds_read_b128 v[158:161], v193 offset:17408
	ds_read_b128 v[172:175], v194 offset:16384
	ds_read_b128 v[176:179], v194 offset:17408
	ds_read_b128 v[202:205], v195 offset:16384
	ds_read_b128 v[206:209], v195 offset:17408
	ds_read_b128 v[210:213], v196 offset:16384
	ds_read_b128 v[214:217], v196 offset:17408
	s_waitcnt vmcnt(4)
	s_barrier
	s_waitcnt lgkmcnt(0)
	v_mfma_f32_16x16x32_bf16 v[62:65], v[134:137], v[154:157], v[62:65]
	v_mfma_f32_16x16x32_bf16 v[58:61], v[142:145], v[154:157], v[58:61]
	v_mfma_f32_16x16x32_bf16 v[54:57], v[134:137], v[172:175], v[54:57]
	v_mfma_f32_16x16x32_bf16 v[50:53], v[142:145], v[172:175], v[50:53]
	v_mfma_f32_16x16x32_bf16 v[46:49], v[134:137], v[202:205], v[46:49]
	v_mfma_f32_16x16x32_bf16 v[42:45], v[142:145], v[202:205], v[42:45]
	v_mfma_f32_16x16x32_bf16 v[38:41], v[134:137], v[210:213], v[38:41]
	v_mfma_f32_16x16x32_bf16 v[34:37], v[142:145], v[210:213], v[34:37]
	v_mfma_f32_16x16x32_bf16 v[62:65], v[138:141], v[158:161], v[62:65]
	v_mfma_f32_16x16x32_bf16 v[58:61], v[150:153], v[158:161], v[58:61]
	v_mfma_f32_16x16x32_bf16 v[54:57], v[138:141], v[176:179], v[54:57]
	v_mfma_f32_16x16x32_bf16 v[50:53], v[150:153], v[176:179], v[50:53]
	v_mfma_f32_16x16x32_bf16 v[46:49], v[138:141], v[206:209], v[46:49]
	v_mfma_f32_16x16x32_bf16 v[42:45], v[150:153], v[206:209], v[42:45]
	v_mfma_f32_16x16x32_bf16 v[38:41], v[138:141], v[214:217], v[38:41]
	v_mfma_f32_16x16x32_bf16 v[34:37], v[150:153], v[214:217], v[34:37]
	v_mfma_f32_16x16x32_bf16 v[30:33], v[130:133], v[154:157], v[30:33]
	v_mfma_f32_16x16x32_bf16 v[26:29], v[218:221], v[154:157], v[26:29]
	v_mfma_f32_16x16x32_bf16 v[22:25], v[130:133], v[172:175], v[22:25]
	v_mfma_f32_16x16x32_bf16 v[18:21], v[218:221], v[172:175], v[18:21]
	v_mfma_f32_16x16x32_bf16 v[14:17], v[130:133], v[202:205], v[14:17]
	v_mfma_f32_16x16x32_bf16 v[10:13], v[218:221], v[202:205], v[10:13]
	v_mfma_f32_16x16x32_bf16 v[6:9], v[130:133], v[210:213], v[6:9]
	v_mfma_f32_16x16x32_bf16 v[2:5], v[218:221], v[210:213], v[2:5]
	v_mfma_f32_16x16x32_bf16 v[30:33], v[146:149], v[158:161], v[30:33]
	v_mfma_f32_16x16x32_bf16 v[26:29], v[222:225], v[158:161], v[26:29]
	v_mfma_f32_16x16x32_bf16 v[22:25], v[146:149], v[176:179], v[22:25]
	v_mfma_f32_16x16x32_bf16 v[18:21], v[222:225], v[176:179], v[18:21]
	v_mfma_f32_16x16x32_bf16 v[14:17], v[146:149], v[206:209], v[14:17]
	v_mfma_f32_16x16x32_bf16 v[10:13], v[222:225], v[206:209], v[10:13]
	v_mfma_f32_16x16x32_bf16 v[6:9], v[146:149], v[214:217], v[6:9]
	v_mfma_f32_16x16x32_bf16 v[2:5], v[222:225], v[214:217], v[2:5]
	s_barrier
	ds_read_b128 v[172:175], v199
	ds_read_b128 v[176:179], v199 offset:1024
	ds_read_b128 v[202:205], v199 offset:2048
	ds_read_b128 v[206:209], v199 offset:3072
	ds_read_b128 v[130:133], v193 offset:32768
	ds_read_b128 v[134:137], v193 offset:33792
	ds_read_b128 v[210:213], v194 offset:32768
	ds_read_b128 v[214:217], v194 offset:33792
	ds_read_b128 v[218:221], v195 offset:32768
	ds_read_b128 v[222:225], v195 offset:33792
	ds_read_b128 v[226:229], v196 offset:32768
	ds_read_b128 v[230:233], v196 offset:33792
	s_waitcnt vmcnt(2)
	s_barrier
	s_waitcnt lgkmcnt(0)
	v_mfma_f32_16x16x32_bf16 v[126:129], v[172:175], v[130:133], v[126:129]
	v_mfma_f32_16x16x32_bf16 v[122:125], v[202:205], v[130:133], v[122:125]
	v_mfma_f32_16x16x32_bf16 v[118:121], v[172:175], v[210:213], v[118:121]
	v_mfma_f32_16x16x32_bf16 v[114:117], v[202:205], v[210:213], v[114:117]
	v_mfma_f32_16x16x32_bf16 v[110:113], v[172:175], v[218:221], v[110:113]
	v_mfma_f32_16x16x32_bf16 v[106:109], v[202:205], v[218:221], v[106:109]
	v_mfma_f32_16x16x32_bf16 v[102:105], v[172:175], v[226:229], v[102:105]
	v_mfma_f32_16x16x32_bf16 v[98:101], v[202:205], v[226:229], v[98:101]
	v_mfma_f32_16x16x32_bf16 v[158:161], v[176:179], v[134:137], v[126:129]
	v_mfma_f32_16x16x32_bf16 v[154:157], v[206:209], v[134:137], v[122:125]
	v_mfma_f32_16x16x32_bf16 v[142:145], v[176:179], v[214:217], v[118:121]
	v_mfma_f32_16x16x32_bf16 v[138:141], v[206:209], v[214:217], v[114:117]
	v_mfma_f32_16x16x32_bf16 v[126:129], v[176:179], v[222:225], v[110:113]
	v_mfma_f32_16x16x32_bf16 v[122:125], v[206:209], v[222:225], v[106:109]
	v_mfma_f32_16x16x32_bf16 v[110:113], v[176:179], v[230:233], v[102:105]
	v_mfma_f32_16x16x32_bf16 v[106:109], v[206:209], v[230:233], v[98:101]
	s_barrier
	ds_read_b128 v[234:237], v200
	ds_read_b128 v[238:241], v200 offset:1024
	ds_read_b128 v[242:245], v200 offset:2048
	ds_read_b128 v[246:249], v200 offset:3072
	s_waitcnt vmcnt(0)
	s_barrier
	s_waitcnt lgkmcnt(0)
	v_mfma_f32_16x16x32_bf16 v[94:97], v[234:237], v[130:133], v[94:97]
	v_mfma_f32_16x16x32_bf16 v[90:93], v[242:245], v[130:133], v[90:93]
	v_mfma_f32_16x16x32_bf16 v[86:89], v[234:237], v[210:213], v[86:89]
	v_mfma_f32_16x16x32_bf16 v[82:85], v[242:245], v[210:213], v[82:85]
	v_mfma_f32_16x16x32_bf16 v[78:81], v[234:237], v[218:221], v[78:81]
	v_mfma_f32_16x16x32_bf16 v[74:77], v[242:245], v[218:221], v[74:77]
	v_mfma_f32_16x16x32_bf16 v[70:73], v[234:237], v[226:229], v[70:73]
	v_mfma_f32_16x16x32_bf16 v[66:69], v[242:245], v[226:229], v[66:69]
	v_mfma_f32_16x16x32_bf16 v[150:153], v[238:241], v[134:137], v[94:97]
	v_mfma_f32_16x16x32_bf16 v[146:149], v[246:249], v[134:137], v[90:93]
	v_mfma_f32_16x16x32_bf16 v[134:137], v[238:241], v[214:217], v[86:89]
	v_mfma_f32_16x16x32_bf16 v[130:133], v[246:249], v[214:217], v[82:85]
	v_mfma_f32_16x16x32_bf16 v[118:121], v[238:241], v[222:225], v[78:81]
	v_mfma_f32_16x16x32_bf16 v[114:117], v[246:249], v[222:225], v[74:77]
	v_mfma_f32_16x16x32_bf16 v[102:105], v[238:241], v[230:233], v[70:73]
	v_mfma_f32_16x16x32_bf16 v[98:101], v[246:249], v[230:233], v[66:69]
	s_barrier
	s_nop 0
	ds_read_b128 v[66:69], v193 offset:49152
	ds_read_b128 v[70:73], v193 offset:50176
	ds_read_b128 v[210:213], v194 offset:49152
	ds_read_b128 v[214:217], v194 offset:50176
	ds_read_b128 v[218:221], v195 offset:49152
	ds_read_b128 v[222:225], v195 offset:50176
	ds_read_b128 v[226:229], v196 offset:49152
	ds_read_b128 v[230:233], v196 offset:50176
	s_barrier
	s_waitcnt lgkmcnt(0)
	v_mfma_f32_16x16x32_bf16 v[62:65], v[172:175], v[66:69], v[62:65]
	v_mfma_f32_16x16x32_bf16 v[58:61], v[202:205], v[66:69], v[58:61]
	v_mfma_f32_16x16x32_bf16 v[54:57], v[172:175], v[210:213], v[54:57]
	v_mfma_f32_16x16x32_bf16 v[50:53], v[202:205], v[210:213], v[50:53]
	v_mfma_f32_16x16x32_bf16 v[46:49], v[172:175], v[218:221], v[46:49]
	v_mfma_f32_16x16x32_bf16 v[42:45], v[202:205], v[218:221], v[42:45]
	v_mfma_f32_16x16x32_bf16 v[38:41], v[172:175], v[226:229], v[38:41]
	v_mfma_f32_16x16x32_bf16 v[34:37], v[202:205], v[226:229], v[34:37]
	v_mfma_f32_16x16x32_bf16 v[94:97], v[176:179], v[70:73], v[62:65]
	v_mfma_f32_16x16x32_bf16 v[90:93], v[206:209], v[70:73], v[58:61]
	v_mfma_f32_16x16x32_bf16 v[78:81], v[176:179], v[214:217], v[54:57]
	v_mfma_f32_16x16x32_bf16 v[74:77], v[206:209], v[214:217], v[50:53]
	v_mfma_f32_16x16x32_bf16 v[62:65], v[176:179], v[222:225], v[46:49]
	v_mfma_f32_16x16x32_bf16 v[58:61], v[206:209], v[222:225], v[42:45]
	v_mfma_f32_16x16x32_bf16 v[46:49], v[176:179], v[230:233], v[38:41]
	v_mfma_f32_16x16x32_bf16 v[42:45], v[206:209], v[230:233], v[34:37]
	v_mfma_f32_16x16x32_bf16 v[30:33], v[234:237], v[66:69], v[30:33]
	v_mfma_f32_16x16x32_bf16 v[26:29], v[242:245], v[66:69], v[26:29]
	v_mfma_f32_16x16x32_bf16 v[22:25], v[234:237], v[210:213], v[22:25]
	v_mfma_f32_16x16x32_bf16 v[18:21], v[242:245], v[210:213], v[18:21]
	v_mfma_f32_16x16x32_bf16 v[14:17], v[234:237], v[218:221], v[14:17]
	v_mfma_f32_16x16x32_bf16 v[10:13], v[242:245], v[218:221], v[10:13]
	v_mfma_f32_16x16x32_bf16 v[6:9], v[234:237], v[226:229], v[6:9]
	v_mfma_f32_16x16x32_bf16 v[2:5], v[242:245], v[226:229], v[2:5]
	v_mfma_f32_16x16x32_bf16 v[86:89], v[238:241], v[70:73], v[30:33]
	v_mfma_f32_16x16x32_bf16 v[82:85], v[246:249], v[70:73], v[26:29]
	v_mfma_f32_16x16x32_bf16 v[70:73], v[238:241], v[214:217], v[22:25]
	v_mfma_f32_16x16x32_bf16 v[66:69], v[246:249], v[214:217], v[18:21]
	v_mfma_f32_16x16x32_bf16 v[54:57], v[238:241], v[222:225], v[14:17]
	v_mfma_f32_16x16x32_bf16 v[50:53], v[246:249], v[222:225], v[10:13]
	v_mfma_f32_16x16x32_bf16 v[38:41], v[238:241], v[230:233], v[6:9]
	v_mfma_f32_16x16x32_bf16 v[34:37], v[246:249], v[230:233], v[2:5]
	s_barrier
	s_and_saveexec_b64 s[62:63], s[6:7]
	s_cbranch_execz .LBB0_2362
	s_barrier

.LBB0_2580:
	ds_read_b128 v[176:179], v168
	ds_read_b128 v[180:183], v168 offset:1024
	ds_read_b128 v[184:187], v168 offset:2048
	ds_read_b128 v[188:191], v168 offset:3072
	v_add_u32_e32 v161, 0xc000, v149
	v_lshl_add_u64 v[164:165], s[36:37], 0, v[144:145]
	v_readfirstlane_b32 s39, v161
	v_lshl_add_u64 v[162:163], v[164:165], 0, s[16:17]
	s_mov_b32 m0, s39
	ds_read_b128 v[192:195], v169
	ds_read_b128 v[200:203], v169 offset:1024
	ds_read_b128 v[204:207], v170
	ds_read_b128 v[208:211], v170 offset:1024
	ds_read_b128 v[212:215], v171
	ds_read_b128 v[216:219], v171 offset:1024
	ds_read_b128 v[220:223], v172
	ds_read_b128 v[224:227], v172 offset:1024
	global_load_lds_dwordx4 v[162:163], off
	v_add_u32_e32 v162, 0xe000, v149
	v_lshl_add_u64 v[196:197], s[36:37], 0, v[146:147]
	v_readfirstlane_b32 s39, v162
	v_lshl_add_u64 v[228:229], v[196:197], 0, s[16:17]
	s_mov_b32 m0, s39
	s_nop 0
	global_load_lds_dwordx4 v[228:229], off
	s_waitcnt lgkmcnt(8)
	s_barrier
	s_waitcnt lgkmcnt(0)
	v_mfma_f32_16x16x32_bf16 v[126:129], v[176:179], v[192:195], v[126:129]
	v_mfma_f32_16x16x32_bf16 v[122:125], v[184:187], v[192:195], v[122:125]
	v_mfma_f32_16x16x32_bf16 v[118:121], v[176:179], v[204:207], v[118:121]
	v_mfma_f32_16x16x32_bf16 v[114:117], v[184:187], v[204:207], v[114:117]
	v_mfma_f32_16x16x32_bf16 v[110:113], v[176:179], v[212:215], v[110:113]
	v_mfma_f32_16x16x32_bf16 v[106:109], v[184:187], v[212:215], v[106:109]
	v_mfma_f32_16x16x32_bf16 v[102:105], v[176:179], v[220:223], v[102:105]
	v_mfma_f32_16x16x32_bf16 v[98:101], v[184:187], v[220:223], v[98:101]
	v_mfma_f32_16x16x32_bf16 v[126:129], v[180:183], v[200:203], v[126:129]
	v_mfma_f32_16x16x32_bf16 v[122:125], v[188:191], v[200:203], v[122:125]
	v_mfma_f32_16x16x32_bf16 v[118:121], v[180:183], v[208:211], v[118:121]
	v_mfma_f32_16x16x32_bf16 v[114:117], v[188:191], v[208:211], v[114:117]
	v_mfma_f32_16x16x32_bf16 v[110:113], v[180:183], v[216:219], v[110:113]
	v_mfma_f32_16x16x32_bf16 v[106:109], v[188:191], v[216:219], v[106:109]
	v_mfma_f32_16x16x32_bf16 v[102:105], v[180:183], v[224:227], v[102:105]
	v_mfma_f32_16x16x32_bf16 v[98:101], v[188:191], v[224:227], v[98:101]
	s_barrier
	v_lshl_add_u64 v[244:245], s[36:37], 0, v[140:141]
	v_readfirstlane_b32 s39, v134
	v_lshl_add_u64 v[246:247], v[244:245], 0, s[18:19]
	s_mov_b32 m0, s39
	ds_read_b128 v[228:231], v173
	ds_read_b128 v[232:235], v173 offset:1024
	ds_read_b128 v[236:239], v173 offset:2048
	ds_read_b128 v[240:243], v173 offset:3072
	global_load_lds_dwordx4 v[246:247], off
	v_lshl_add_u64 v[246:247], s[36:37], 0, v[142:143]
	v_readfirstlane_b32 s39, v148
	v_lshl_add_u64 v[248:249], v[246:247], 0, s[18:19]
	s_mov_b32 m0, s39
	s_nop 0
	global_load_lds_dwordx4 v[248:249], off
	s_barrier
	s_waitcnt lgkmcnt(0)
	v_mfma_f32_16x16x32_bf16 v[94:97], v[228:231], v[192:195], v[94:97]
	v_mfma_f32_16x16x32_bf16 v[90:93], v[236:239], v[192:195], v[90:93]
	v_mfma_f32_16x16x32_bf16 v[86:89], v[228:231], v[204:207], v[86:89]
	v_mfma_f32_16x16x32_bf16 v[82:85], v[236:239], v[204:207], v[82:85]
	v_mfma_f32_16x16x32_bf16 v[78:81], v[228:231], v[212:215], v[78:81]
	v_mfma_f32_16x16x32_bf16 v[74:77], v[236:239], v[212:215], v[74:77]
	v_mfma_f32_16x16x32_bf16 v[70:73], v[228:231], v[220:223], v[70:73]
	v_mfma_f32_16x16x32_bf16 v[66:69], v[236:239], v[220:223], v[66:69]
	v_mfma_f32_16x16x32_bf16 v[94:97], v[232:235], v[200:203], v[94:97]
	v_mfma_f32_16x16x32_bf16 v[90:93], v[240:243], v[200:203], v[90:93]
	v_mfma_f32_16x16x32_bf16 v[86:89], v[232:235], v[208:211], v[86:89]
	v_mfma_f32_16x16x32_bf16 v[82:85], v[240:243], v[208:211], v[82:85]
	v_mfma_f32_16x16x32_bf16 v[78:81], v[232:235], v[216:219], v[78:81]
	v_mfma_f32_16x16x32_bf16 v[74:77], v[240:243], v[216:219], v[74:77]
	v_mfma_f32_16x16x32_bf16 v[70:73], v[232:235], v[224:227], v[70:73]
	v_mfma_f32_16x16x32_bf16 v[66:69], v[240:243], v[224:227], v[66:69]
	v_readfirstlane_b32 s39, v149
	v_lshl_add_u64 v[248:249], v[164:165], 0, s[20:21]
	s_mov_b32 m0, s39
	v_readfirstlane_b32 s39, v150
	s_barrier
	ds_read_b128 v[192:195], v169 offset:16384
	ds_read_b128 v[200:203], v169 offset:17408
	ds_read_b128 v[204:207], v170 offset:16384
	ds_read_b128 v[208:211], v170 offset:17408
	ds_read_b128 v[212:215], v171 offset:16384
	ds_read_b128 v[216:219], v171 offset:17408
	ds_read_b128 v[220:223], v172 offset:16384
	ds_read_b128 v[224:227], v172 offset:17408
	global_load_lds_dwordx4 v[248:249], off
	v_lshl_add_u64 v[248:249], v[196:197], 0, s[20:21]
	s_mov_b32 m0, s39
	s_nop 0
	global_load_lds_dwordx4 v[248:249], off
	s_barrier
	s_waitcnt lgkmcnt(0)
	v_mfma_f32_16x16x32_bf16 v[62:65], v[176:179], v[192:195], v[62:65]
	v_mfma_f32_16x16x32_bf16 v[58:61], v[184:187], v[192:195], v[58:61]
	v_mfma_f32_16x16x32_bf16 v[54:57], v[176:179], v[204:207], v[54:57]
	v_mfma_f32_16x16x32_bf16 v[50:53], v[184:187], v[204:207], v[50:53]
	v_mfma_f32_16x16x32_bf16 v[46:49], v[176:179], v[212:215], v[46:49]
	v_mfma_f32_16x16x32_bf16 v[42:45], v[184:187], v[212:215], v[42:45]
	v_mfma_f32_16x16x32_bf16 v[38:41], v[176:179], v[220:223], v[38:41]
	v_mfma_f32_16x16x32_bf16 v[34:37], v[184:187], v[220:223], v[34:37]
	v_mfma_f32_16x16x32_bf16 v[62:65], v[180:183], v[200:203], v[62:65]
	v_mfma_f32_16x16x32_bf16 v[58:61], v[188:191], v[200:203], v[58:61]
	v_mfma_f32_16x16x32_bf16 v[54:57], v[180:183], v[208:211], v[54:57]
	v_mfma_f32_16x16x32_bf16 v[50:53], v[188:191], v[208:211], v[50:53]
	v_mfma_f32_16x16x32_bf16 v[46:49], v[180:183], v[216:219], v[46:49]
	v_mfma_f32_16x16x32_bf16 v[42:45], v[188:191], v[216:219], v[42:45]
	v_mfma_f32_16x16x32_bf16 v[38:41], v[180:183], v[224:227], v[38:41]
	v_mfma_f32_16x16x32_bf16 v[34:37], v[188:191], v[224:227], v[34:37]
	s_barrier
	v_readfirstlane_b32 s39, v151
	v_lshl_add_u64 v[176:177], v[244:245], 0, s[22:23]
	s_mov_b32 m0, s39
	v_readfirstlane_b32 s39, v152
	global_load_lds_dwordx4 v[176:177], off
	v_lshl_add_u64 v[176:177], v[246:247], 0, s[22:23]
	s_mov_b32 m0, s39
	s_nop 0
	global_load_lds_dwordx4 v[176:177], off
	s_waitcnt vmcnt(6)
	s_barrier
	v_mfma_f32_16x16x32_bf16 v[30:33], v[228:231], v[192:195], v[30:33]
	v_mfma_f32_16x16x32_bf16 v[26:29], v[236:239], v[192:195], v[26:29]
	v_mfma_f32_16x16x32_bf16 v[22:25], v[228:231], v[204:207], v[22:25]
	v_mfma_f32_16x16x32_bf16 v[18:21], v[236:239], v[204:207], v[18:21]
	v_mfma_f32_16x16x32_bf16 v[14:17], v[228:231], v[212:215], v[14:17]
	v_mfma_f32_16x16x32_bf16 v[10:13], v[236:239], v[212:215], v[10:13]
	v_mfma_f32_16x16x32_bf16 v[6:9], v[228:231], v[220:223], v[6:9]
	v_mfma_f32_16x16x32_bf16 v[2:5], v[236:239], v[220:223], v[2:5]
	v_mfma_f32_16x16x32_bf16 v[30:33], v[232:235], v[200:203], v[30:33]
	v_mfma_f32_16x16x32_bf16 v[26:29], v[240:243], v[200:203], v[26:29]
	v_mfma_f32_16x16x32_bf16 v[22:25], v[232:235], v[208:211], v[22:25]
	v_mfma_f32_16x16x32_bf16 v[18:21], v[240:243], v[208:211], v[18:21]
	v_mfma_f32_16x16x32_bf16 v[14:17], v[232:235], v[216:219], v[14:17]
	v_mfma_f32_16x16x32_bf16 v[10:13], v[240:243], v[216:219], v[10:13]
	v_mfma_f32_16x16x32_bf16 v[6:9], v[232:235], v[224:227], v[6:9]
	v_mfma_f32_16x16x32_bf16 v[2:5], v[240:243], v[224:227], v[2:5]
	s_barrier
	ds_read_b128 v[176:179], v174
	ds_read_b128 v[180:183], v174 offset:1024
	ds_read_b128 v[184:187], v174 offset:2048
	ds_read_b128 v[188:191], v174 offset:3072
	v_readfirstlane_b32 s39, v153
	v_lshl_add_u64 v[228:229], v[164:165], 0, s[24:25]
	s_mov_b32 m0, s39
	v_readfirstlane_b32 s39, v154
	ds_read_b128 v[192:195], v169 offset:32768
	ds_read_b128 v[200:203], v169 offset:33792
	ds_read_b128 v[204:207], v170 offset:32768
	ds_read_b128 v[208:211], v170 offset:33792
	ds_read_b128 v[212:215], v171 offset:32768
	ds_read_b128 v[216:219], v171 offset:33792
	ds_read_b128 v[220:223], v172 offset:32768
	ds_read_b128 v[224:227], v172 offset:33792
	global_load_lds_dwordx4 v[228:229], off
	v_lshl_add_u64 v[228:229], v[196:197], 0, s[24:25]
	s_mov_b32 m0, s39
	s_nop 0
	global_load_lds_dwordx4 v[228:229], off
	s_waitcnt lgkmcnt(8)
	s_barrier
	s_waitcnt lgkmcnt(0)
	v_mfma_f32_16x16x32_bf16 v[126:129], v[176:179], v[192:195], v[126:129]
	v_mfma_f32_16x16x32_bf16 v[122:125], v[184:187], v[192:195], v[122:125]
	v_mfma_f32_16x16x32_bf16 v[118:121], v[176:179], v[204:207], v[118:121]
	v_mfma_f32_16x16x32_bf16 v[114:117], v[184:187], v[204:207], v[114:117]
	v_mfma_f32_16x16x32_bf16 v[110:113], v[176:179], v[212:215], v[110:113]
	v_mfma_f32_16x16x32_bf16 v[106:109], v[184:187], v[212:215], v[106:109]
	v_mfma_f32_16x16x32_bf16 v[102:105], v[176:179], v[220:223], v[102:105]
	v_mfma_f32_16x16x32_bf16 v[98:101], v[184:187], v[220:223], v[98:101]
	v_mfma_f32_16x16x32_bf16 v[126:129], v[180:183], v[200:203], v[126:129]
	v_mfma_f32_16x16x32_bf16 v[122:125], v[188:191], v[200:203], v[122:125]
	v_mfma_f32_16x16x32_bf16 v[118:121], v[180:183], v[208:211], v[118:121]
	v_mfma_f32_16x16x32_bf16 v[114:117], v[188:191], v[208:211], v[114:117]
	v_mfma_f32_16x16x32_bf16 v[110:113], v[180:183], v[216:219], v[110:113]
	v_mfma_f32_16x16x32_bf16 v[106:109], v[188:191], v[216:219], v[106:109]
	v_mfma_f32_16x16x32_bf16 v[102:105], v[180:183], v[224:227], v[102:105]
	v_mfma_f32_16x16x32_bf16 v[98:101], v[188:191], v[224:227], v[98:101]
	s_barrier
	v_readfirstlane_b32 s39, v155
	v_lshl_add_u64 v[248:249], v[244:245], 0, s[26:27]
	s_mov_b32 m0, s39
	v_readfirstlane_b32 s39, v156
	ds_read_b128 v[228:231], v175
	ds_read_b128 v[232:235], v175 offset:1024
	ds_read_b128 v[236:239], v175 offset:2048
	ds_read_b128 v[240:243], v175 offset:3072
	global_load_lds_dwordx4 v[248:249], off
	v_lshl_add_u64 v[248:249], v[246:247], 0, s[26:27]
	s_mov_b32 m0, s39
	s_nop 0
	global_load_lds_dwordx4 v[248:249], off
	s_barrier
	s_waitcnt lgkmcnt(0)
	v_mfma_f32_16x16x32_bf16 v[94:97], v[228:231], v[192:195], v[94:97]
	v_mfma_f32_16x16x32_bf16 v[90:93], v[236:239], v[192:195], v[90:93]
	v_mfma_f32_16x16x32_bf16 v[86:89], v[228:231], v[204:207], v[86:89]
	v_mfma_f32_16x16x32_bf16 v[82:85], v[236:239], v[204:207], v[82:85]
	v_mfma_f32_16x16x32_bf16 v[78:81], v[228:231], v[212:215], v[78:81]
	v_mfma_f32_16x16x32_bf16 v[74:77], v[236:239], v[212:215], v[74:77]
	v_mfma_f32_16x16x32_bf16 v[70:73], v[228:231], v[220:223], v[70:73]
	v_mfma_f32_16x16x32_bf16 v[66:69], v[236:239], v[220:223], v[66:69]
	v_mfma_f32_16x16x32_bf16 v[94:97], v[232:235], v[200:203], v[94:97]
	v_mfma_f32_16x16x32_bf16 v[90:93], v[240:243], v[200:203], v[90:93]
	v_mfma_f32_16x16x32_bf16 v[86:89], v[232:235], v[208:211], v[86:89]
	v_mfma_f32_16x16x32_bf16 v[82:85], v[240:243], v[208:211], v[82:85]
	v_mfma_f32_16x16x32_bf16 v[78:81], v[232:235], v[216:219], v[78:81]
	v_mfma_f32_16x16x32_bf16 v[74:77], v[240:243], v[216:219], v[74:77]
	v_mfma_f32_16x16x32_bf16 v[70:73], v[232:235], v[224:227], v[70:73]
	v_mfma_f32_16x16x32_bf16 v[66:69], v[240:243], v[224:227], v[66:69]
	v_readfirstlane_b32 s39, v157
	v_lshl_add_u64 v[164:165], v[164:165], 0, s[28:29]
	s_mov_b32 m0, s39
	v_readfirstlane_b32 s39, v158
	s_barrier
	ds_read_b128 v[192:195], v169 offset:49152
	ds_read_b128 v[200:203], v169 offset:50176
	ds_read_b128 v[204:207], v170 offset:49152
	ds_read_b128 v[208:211], v170 offset:50176
	ds_read_b128 v[212:215], v171 offset:49152
	ds_read_b128 v[216:219], v171 offset:50176
	ds_read_b128 v[220:223], v172 offset:49152
	ds_read_b128 v[224:227], v172 offset:50176
	global_load_lds_dwordx4 v[164:165], off
	v_lshl_add_u64 v[164:165], v[196:197], 0, s[28:29]
	s_mov_b32 m0, s39
	s_nop 0
	global_load_lds_dwordx4 v[164:165], off
	s_barrier
	s_waitcnt lgkmcnt(0)
	v_mfma_f32_16x16x32_bf16 v[62:65], v[176:179], v[192:195], v[62:65]
	v_mfma_f32_16x16x32_bf16 v[58:61], v[184:187], v[192:195], v[58:61]
	v_mfma_f32_16x16x32_bf16 v[54:57], v[176:179], v[204:207], v[54:57]
	v_mfma_f32_16x16x32_bf16 v[50:53], v[184:187], v[204:207], v[50:53]
	v_mfma_f32_16x16x32_bf16 v[46:49], v[176:179], v[212:215], v[46:49]
	v_mfma_f32_16x16x32_bf16 v[42:45], v[184:187], v[212:215], v[42:45]
	v_mfma_f32_16x16x32_bf16 v[38:41], v[176:179], v[220:223], v[38:41]
	v_mfma_f32_16x16x32_bf16 v[34:37], v[184:187], v[220:223], v[34:37]
	v_mfma_f32_16x16x32_bf16 v[62:65], v[180:183], v[200:203], v[62:65]
	v_mfma_f32_16x16x32_bf16 v[58:61], v[188:191], v[200:203], v[58:61]
	v_mfma_f32_16x16x32_bf16 v[54:57], v[180:183], v[208:211], v[54:57]
	v_mfma_f32_16x16x32_bf16 v[50:53], v[188:191], v[208:211], v[50:53]
	v_mfma_f32_16x16x32_bf16 v[46:49], v[180:183], v[216:219], v[46:49]
	v_mfma_f32_16x16x32_bf16 v[42:45], v[188:191], v[216:219], v[42:45]
	v_mfma_f32_16x16x32_bf16 v[38:41], v[180:183], v[224:227], v[38:41]
	v_mfma_f32_16x16x32_bf16 v[34:37], v[188:191], v[224:227], v[34:37]
	s_barrier
	v_readfirstlane_b32 s39, v159
	v_lshl_add_u64 v[164:165], v[244:245], 0, s[30:31]
	s_mov_b32 m0, s39
	v_readfirstlane_b32 s39, v160
	global_load_lds_dwordx4 v[164:165], off
	v_lshl_add_u64 v[164:165], v[246:247], 0, s[30:31]
	s_mov_b32 m0, s39
	s_nop 0
	global_load_lds_dwordx4 v[164:165], off
	s_waitcnt vmcnt(6)
	s_barrier
	v_mfma_f32_16x16x32_bf16 v[30:33], v[228:231], v[192:195], v[30:33]
	v_mfma_f32_16x16x32_bf16 v[26:29], v[236:239], v[192:195], v[26:29]
	v_mfma_f32_16x16x32_bf16 v[22:25], v[228:231], v[204:207], v[22:25]
	v_mfma_f32_16x16x32_bf16 v[18:21], v[236:239], v[204:207], v[18:21]
	v_mfma_f32_16x16x32_bf16 v[14:17], v[228:231], v[212:215], v[14:17]
	v_mfma_f32_16x16x32_bf16 v[10:13], v[236:239], v[212:215], v[10:13]
	v_mfma_f32_16x16x32_bf16 v[6:9], v[228:231], v[220:223], v[6:9]
	v_mfma_f32_16x16x32_bf16 v[2:5], v[236:239], v[220:223], v[2:5]
	v_mfma_f32_16x16x32_bf16 v[30:33], v[232:235], v[200:203], v[30:33]
	v_mfma_f32_16x16x32_bf16 v[26:29], v[240:243], v[200:203], v[26:29]
	v_mfma_f32_16x16x32_bf16 v[22:25], v[232:235], v[208:211], v[22:25]
	v_mfma_f32_16x16x32_bf16 v[18:21], v[240:243], v[208:211], v[18:21]
	v_mfma_f32_16x16x32_bf16 v[14:17], v[232:235], v[216:219], v[14:17]
	v_mfma_f32_16x16x32_bf16 v[10:13], v[240:243], v[216:219], v[10:13]
	v_mfma_f32_16x16x32_bf16 v[6:9], v[232:235], v[224:227], v[6:9]
	v_mfma_f32_16x16x32_bf16 v[2:5], v[240:243], v[224:227], v[2:5]
	s_add_i32 s38, s38, 2
	s_add_u32 s36, s36, 0x100
	s_addc_u32 s37, s37, 0
	s_cmp_lt_u32 s38, 40
	s_barrier
	s_cbranch_scc1 .LBB0_2580
	s_add_u32 s6, s6, 0x1580
	s_addc_u32 s7, s7, 0
	v_readfirstlane_b32 s36, v161
	v_lshl_add_u64 v[164:165], s[6:7], 0, v[132:133]
	s_mov_b32 m0, s36
	v_lshl_add_u64 v[160:161], s[6:7], 0, v[130:131]
	v_readfirstlane_b32 s6, v162
	ds_read_b128 v[140:143], v168
	ds_read_b128 v[144:147], v168 offset:1024
	ds_read_b128 v[148:151], v168 offset:2048
	ds_read_b128 v[152:155], v168 offset:3072
	ds_read_b128 v[156:159], v169
	ds_read_b128 v[176:179], v169 offset:1024
	ds_read_b128 v[180:183], v170
	ds_read_b128 v[184:187], v170 offset:1024
	ds_read_b128 v[188:191], v171
	ds_read_b128 v[192:195], v171 offset:1024
	ds_read_b128 v[200:203], v172
	ds_read_b128 v[204:207], v172 offset:1024
	global_load_lds_dwordx4 v[164:165], off
	s_mov_b32 m0, s6
	s_nop 0
	global_load_lds_dwordx4 v[160:161], off
	s_barrier
	s_waitcnt lgkmcnt(0)
	v_mfma_f32_16x16x32_bf16 v[126:129], v[140:143], v[156:159], v[126:129]
	v_mfma_f32_16x16x32_bf16 v[122:125], v[148:151], v[156:159], v[122:125]
	v_mfma_f32_16x16x32_bf16 v[110:113], v[140:143], v[188:191], v[110:113]
	v_mfma_f32_16x16x32_bf16 v[106:109], v[148:151], v[188:191], v[106:109]
	v_mfma_f32_16x16x32_bf16 v[126:129], v[144:147], v[176:179], v[126:129]
	v_mfma_f32_16x16x32_bf16 v[122:125], v[152:155], v[176:179], v[122:125]
	v_mfma_f32_16x16x32_bf16 v[118:121], v[140:143], v[180:183], v[118:121]
	v_mfma_f32_16x16x32_bf16 v[114:117], v[148:151], v[180:183], v[114:117]
	v_mfma_f32_16x16x32_bf16 v[110:113], v[144:147], v[192:195], v[110:113]
	v_mfma_f32_16x16x32_bf16 v[106:109], v[152:155], v[192:195], v[106:109]
	v_mfma_f32_16x16x32_bf16 v[102:105], v[140:143], v[200:203], v[102:105]
	v_mfma_f32_16x16x32_bf16 v[98:101], v[148:151], v[200:203], v[98:101]
	v_mfma_f32_16x16x32_bf16 v[160:163], v[144:147], v[184:187], v[118:121]
	v_mfma_f32_16x16x32_bf16 v[208:211], v[152:155], v[184:187], v[114:117]
	v_mfma_f32_16x16x32_bf16 v[212:215], v[144:147], v[204:207], v[102:105]
	v_mfma_f32_16x16x32_bf16 v[216:219], v[152:155], v[204:207], v[98:101]
	s_barrier
	s_nop 1
	ds_read_b128 v[98:101], v173
	ds_read_b128 v[102:105], v173 offset:1024
	ds_read_b128 v[114:117], v173 offset:2048
	ds_read_b128 v[118:121], v173 offset:3072
	s_barrier
	s_waitcnt lgkmcnt(0)
	v_mfma_f32_16x16x32_bf16 v[94:97], v[98:101], v[156:159], v[94:97]
	v_mfma_f32_16x16x32_bf16 v[90:93], v[114:117], v[156:159], v[90:93]
	v_mfma_f32_16x16x32_bf16 v[78:81], v[98:101], v[188:191], v[78:81]
	v_mfma_f32_16x16x32_bf16 v[74:77], v[114:117], v[188:191], v[74:77]
	v_mfma_f32_16x16x32_bf16 v[94:97], v[102:105], v[176:179], v[94:97]
	v_mfma_f32_16x16x32_bf16 v[90:93], v[118:121], v[176:179], v[90:93]
	v_mfma_f32_16x16x32_bf16 v[86:89], v[98:101], v[180:183], v[86:89]
	v_mfma_f32_16x16x32_bf16 v[82:85], v[114:117], v[180:183], v[82:85]
	v_mfma_f32_16x16x32_bf16 v[78:81], v[102:105], v[192:195], v[78:81]
	v_mfma_f32_16x16x32_bf16 v[74:77], v[118:121], v[192:195], v[74:77]
	v_mfma_f32_16x16x32_bf16 v[70:73], v[98:101], v[200:203], v[70:73]
	v_mfma_f32_16x16x32_bf16 v[66:69], v[114:117], v[200:203], v[66:69]
	v_mfma_f32_16x16x32_bf16 v[156:159], v[102:105], v[184:187], v[86:89]
	v_mfma_f32_16x16x32_bf16 v[176:179], v[118:121], v[184:187], v[82:85]
	v_mfma_f32_16x16x32_bf16 v[180:183], v[102:105], v[204:207], v[70:73]
	v_mfma_f32_16x16x32_bf16 v[184:187], v[118:121], v[204:207], v[66:69]
	s_barrier
	s_nop 1
	ds_read_b128 v[66:69], v169 offset:16384
	ds_read_b128 v[70:73], v169 offset:17408
	ds_read_b128 v[82:85], v170 offset:16384
	ds_read_b128 v[86:89], v170 offset:17408
	ds_read_b128 v[188:191], v171 offset:16384
	ds_read_b128 v[192:195], v171 offset:17408
	ds_read_b128 v[200:203], v172 offset:16384
	ds_read_b128 v[204:207], v172 offset:17408
	s_waitcnt vmcnt(4)
	s_barrier
	s_waitcnt lgkmcnt(0)
	v_mfma_f32_16x16x32_bf16 v[62:65], v[140:143], v[66:69], v[62:65]
	v_mfma_f32_16x16x32_bf16 v[58:61], v[148:151], v[66:69], v[58:61]
	v_mfma_f32_16x16x32_bf16 v[46:49], v[140:143], v[188:191], v[46:49]
	v_mfma_f32_16x16x32_bf16 v[42:45], v[148:151], v[188:191], v[42:45]
	v_mfma_f32_16x16x32_bf16 v[62:65], v[144:147], v[70:73], v[62:65]
	v_mfma_f32_16x16x32_bf16 v[58:61], v[152:155], v[70:73], v[58:61]
	v_mfma_f32_16x16x32_bf16 v[54:57], v[140:143], v[82:85], v[54:57]
	v_mfma_f32_16x16x32_bf16 v[50:53], v[148:151], v[82:85], v[50:53]
	v_mfma_f32_16x16x32_bf16 v[46:49], v[144:147], v[192:195], v[46:49]
	v_mfma_f32_16x16x32_bf16 v[42:45], v[152:155], v[192:195], v[42:45]
	v_mfma_f32_16x16x32_bf16 v[38:41], v[140:143], v[200:203], v[38:41]
	v_mfma_f32_16x16x32_bf16 v[34:37], v[148:151], v[200:203], v[34:37]
	v_mfma_f32_16x16x32_bf16 v[220:223], v[144:147], v[86:89], v[54:57]
	v_mfma_f32_16x16x32_bf16 v[224:227], v[152:155], v[86:89], v[50:53]
	v_mfma_f32_16x16x32_bf16 v[140:143], v[144:147], v[204:207], v[38:41]
	v_mfma_f32_16x16x32_bf16 v[144:147], v[152:155], v[204:207], v[34:37]
	v_mfma_f32_16x16x32_bf16 v[30:33], v[98:101], v[66:69], v[30:33]
	v_mfma_f32_16x16x32_bf16 v[26:29], v[114:117], v[66:69], v[26:29]
	v_mfma_f32_16x16x32_bf16 v[14:17], v[98:101], v[188:191], v[14:17]
	v_mfma_f32_16x16x32_bf16 v[10:13], v[114:117], v[188:191], v[10:13]
	v_mfma_f32_16x16x32_bf16 v[30:33], v[102:105], v[70:73], v[30:33]
	v_mfma_f32_16x16x32_bf16 v[26:29], v[118:121], v[70:73], v[26:29]
	v_mfma_f32_16x16x32_bf16 v[22:25], v[98:101], v[82:85], v[22:25]
	v_mfma_f32_16x16x32_bf16 v[18:21], v[114:117], v[82:85], v[18:21]
	v_mfma_f32_16x16x32_bf16 v[14:17], v[102:105], v[192:195], v[14:17]
	v_mfma_f32_16x16x32_bf16 v[10:13], v[118:121], v[192:195], v[10:13]
	v_mfma_f32_16x16x32_bf16 v[6:9], v[98:101], v[200:203], v[6:9]
	v_mfma_f32_16x16x32_bf16 v[2:5], v[114:117], v[200:203], v[2:5]
	v_mfma_f32_16x16x32_bf16 v[148:151], v[102:105], v[86:89], v[22:25]
	v_mfma_f32_16x16x32_bf16 v[152:155], v[118:121], v[86:89], v[18:21]
	v_mfma_f32_16x16x32_bf16 v[188:191], v[102:105], v[204:207], v[6:9]
	v_mfma_f32_16x16x32_bf16 v[192:195], v[118:121], v[204:207], v[2:5]
	s_barrier
	s_nop 1
	ds_read_b128 v[2:5], v174
	ds_read_b128 v[6:9], v174 offset:1024
	ds_read_b128 v[200:203], v174 offset:2048
	ds_read_b128 v[204:207], v174 offset:3072
	ds_read_b128 v[18:21], v169 offset:32768
	ds_read_b128 v[22:25], v169 offset:33792
	ds_read_b128 v[34:37], v170 offset:32768
	ds_read_b128 v[38:41], v170 offset:33792
	ds_read_b128 v[50:53], v171 offset:32768
	ds_read_b128 v[54:57], v171 offset:33792
	ds_read_b128 v[228:231], v172 offset:32768
	ds_read_b128 v[232:235], v172 offset:33792
	s_waitcnt vmcnt(2)
	s_barrier
	s_waitcnt lgkmcnt(0)
	v_mfma_f32_16x16x32_bf16 v[66:69], v[2:5], v[18:21], v[126:129]
	v_mfma_f32_16x16x32_bf16 v[114:117], v[6:9], v[22:25], v[66:69]
	v_mfma_f32_16x16x32_bf16 v[66:69], v[200:203], v[18:21], v[122:125]
	v_mfma_f32_16x16x32_bf16 v[118:121], v[204:207], v[22:25], v[66:69]
	v_mfma_f32_16x16x32_bf16 v[66:69], v[2:5], v[34:37], v[160:163]
	v_mfma_f32_16x16x32_bf16 v[98:101], v[6:9], v[38:41], v[66:69]
	v_mfma_f32_16x16x32_bf16 v[66:69], v[200:203], v[34:37], v[208:211]
	v_mfma_f32_16x16x32_bf16 v[102:105], v[204:207], v[38:41], v[66:69]
	v_mfma_f32_16x16x32_bf16 v[66:69], v[2:5], v[50:53], v[110:113]
	v_mfma_f32_16x16x32_bf16 v[82:85], v[6:9], v[54:57], v[66:69]
	v_mfma_f32_16x16x32_bf16 v[66:69], v[200:203], v[50:53], v[106:109]
	v_mfma_f32_16x16x32_bf16 v[86:89], v[204:207], v[54:57], v[66:69]
	v_mfma_f32_16x16x32_bf16 v[66:69], v[2:5], v[228:231], v[212:215]
	v_mfma_f32_16x16x32_bf16 v[70:73], v[200:203], v[228:231], v[216:219]
	v_mfma_f32_16x16x32_bf16 v[66:69], v[6:9], v[232:235], v[66:69]
	v_mfma_f32_16x16x32_bf16 v[70:73], v[204:207], v[232:235], v[70:73]
	s_barrier
	ds_read_b128 v[160:163], v175
	ds_read_b128 v[208:211], v175 offset:1024
	ds_read_b128 v[212:215], v175 offset:2048
	ds_read_b128 v[216:219], v175 offset:3072
	s_waitcnt vmcnt(0)
	s_barrier
	s_waitcnt lgkmcnt(0)
	v_mfma_f32_16x16x32_bf16 v[94:97], v[160:163], v[18:21], v[94:97]
	v_mfma_f32_16x16x32_bf16 v[18:21], v[212:215], v[18:21], v[90:93]
	v_mfma_f32_16x16x32_bf16 v[122:125], v[216:219], v[22:25], v[18:21]
	v_mfma_f32_16x16x32_bf16 v[18:21], v[160:163], v[34:37], v[156:159]
	v_mfma_f32_16x16x32_bf16 v[110:113], v[208:211], v[38:41], v[18:21]
	v_mfma_f32_16x16x32_bf16 v[18:21], v[212:215], v[34:37], v[176:179]
	v_mfma_f32_16x16x32_bf16 v[106:109], v[216:219], v[38:41], v[18:21]
	v_mfma_f32_16x16x32_bf16 v[18:21], v[160:163], v[50:53], v[78:81]
	v_mfma_f32_16x16x32_bf16 v[126:129], v[208:211], v[22:25], v[94:97]
	v_mfma_f32_16x16x32_bf16 v[94:97], v[208:211], v[54:57], v[18:21]
	v_mfma_f32_16x16x32_bf16 v[18:21], v[212:215], v[50:53], v[74:77]
	v_mfma_f32_16x16x32_bf16 v[90:93], v[216:219], v[54:57], v[18:21]
	v_mfma_f32_16x16x32_bf16 v[18:21], v[160:163], v[228:231], v[180:183]
	v_mfma_f32_16x16x32_bf16 v[78:81], v[208:211], v[232:235], v[18:21]
	v_mfma_f32_16x16x32_bf16 v[18:21], v[212:215], v[228:231], v[184:187]
	v_mfma_f32_16x16x32_bf16 v[74:77], v[216:219], v[232:235], v[18:21]
	s_barrier
	ds_read_b128 v[156:159], v169 offset:49152
	ds_read_b128 v[176:179], v169 offset:50176
	ds_read_b128 v[180:183], v170 offset:49152
	ds_read_b128 v[184:187], v170 offset:50176
	ds_read_b128 v[228:231], v171 offset:49152
	ds_read_b128 v[232:235], v171 offset:50176
	ds_read_b128 v[236:239], v172 offset:49152
	ds_read_b128 v[240:243], v172 offset:50176
	s_barrier
	s_waitcnt lgkmcnt(0)
	v_mfma_f32_16x16x32_bf16 v[18:21], v[2:5], v[156:159], v[62:65]
	v_mfma_f32_16x16x32_bf16 v[50:53], v[6:9], v[176:179], v[18:21]
	v_mfma_f32_16x16x32_bf16 v[18:21], v[200:203], v[156:159], v[58:61]
	v_mfma_f32_16x16x32_bf16 v[54:57], v[204:207], v[176:179], v[18:21]
	v_mfma_f32_16x16x32_bf16 v[18:21], v[2:5], v[180:183], v[220:223]
	v_mfma_f32_16x16x32_bf16 v[34:37], v[6:9], v[184:187], v[18:21]
	v_mfma_f32_16x16x32_bf16 v[18:21], v[200:203], v[180:183], v[224:227]
	v_mfma_f32_16x16x32_bf16 v[38:41], v[204:207], v[184:187], v[18:21]
	v_mfma_f32_16x16x32_bf16 v[18:21], v[2:5], v[228:231], v[46:49]
	v_mfma_f32_16x16x32_bf16 v[2:5], v[2:5], v[236:239], v[140:143]
	v_mfma_f32_16x16x32_bf16 v[18:21], v[6:9], v[232:235], v[18:21]
	v_mfma_f32_16x16x32_bf16 v[22:25], v[200:203], v[228:231], v[42:45]
	v_mfma_f32_16x16x32_bf16 v[2:5], v[6:9], v[240:243], v[2:5]
	v_mfma_f32_16x16x32_bf16 v[6:9], v[200:203], v[236:239], v[144:147]
	v_mfma_f32_16x16x32_bf16 v[22:25], v[204:207], v[232:235], v[22:25]
	v_mfma_f32_16x16x32_bf16 v[6:9], v[204:207], v[240:243], v[6:9]
	v_mfma_f32_16x16x32_bf16 v[26:29], v[212:215], v[156:159], v[26:29]
	v_mfma_f32_16x16x32_bf16 v[58:61], v[216:219], v[176:179], v[26:29]
	v_mfma_f32_16x16x32_bf16 v[26:29], v[160:163], v[180:183], v[148:151]
	v_mfma_f32_16x16x32_bf16 v[46:49], v[208:211], v[184:187], v[26:29]
	v_mfma_f32_16x16x32_bf16 v[26:29], v[212:215], v[180:183], v[152:155]
	v_mfma_f32_16x16x32_bf16 v[10:13], v[212:215], v[228:231], v[10:13]
	v_mfma_f32_16x16x32_bf16 v[30:33], v[160:163], v[156:159], v[30:33]
	v_mfma_f32_16x16x32_bf16 v[42:45], v[216:219], v[184:187], v[26:29]
	v_mfma_f32_16x16x32_bf16 v[14:17], v[160:163], v[228:231], v[14:17]
	v_mfma_f32_16x16x32_bf16 v[26:29], v[216:219], v[232:235], v[10:13]
	v_mfma_f32_16x16x32_bf16 v[10:13], v[160:163], v[236:239], v[188:191]
	v_mfma_f32_16x16x32_bf16 v[62:65], v[208:211], v[176:179], v[30:33]
	v_mfma_f32_16x16x32_bf16 v[30:33], v[208:211], v[232:235], v[14:17]
	v_mfma_f32_16x16x32_bf16 v[14:17], v[208:211], v[240:243], v[10:13]
	v_mfma_f32_16x16x32_bf16 v[10:13], v[212:215], v[236:239], v[192:195]
	v_mfma_f32_16x16x32_bf16 v[10:13], v[216:219], v[240:243], v[10:13]
	s_barrier
	s_and_saveexec_b64 s[6:7], s[2:3]
	s_cbranch_execz .LBB0_2583
	s_barrier
